# experiment: sc1 write-through dwordx4 stores in the six GEMM phases (to shorten the barrier's L2 writeback)
# baseline (speedup 1.0000x reference)
.LBB0_332:
	v_lshl_add_u32 v154, s26, 8, v148
	v_lshl_or_b32 v156, s70, 8, v150
	v_ashrrev_i32_e32 v155, 31, v154
	v_cvt_pk_bf16_f32 v126, v126, v127
	v_cvt_pk_bf16_f32 v127, v128, v129
	v_cvt_pk_bf16_f32 v128, v122, v123
	v_lshlrev_b64 v[122:123], 13, v[154:155]
	v_ashrrev_i32_e32 v157, 31, v156
	v_cvt_pk_bf16_f32 v129, v124, v125
	v_lshl_add_u64 v[122:123], s[8:9], 0, v[122:123]
	v_lshlrev_b64 v[124:125], 1, v[156:157]
	v_lshl_add_u64 v[122:123], v[122:123], 0, v[124:125]
	v_cvt_pk_bf16_f32 v110, v110, v111
	v_cvt_pk_bf16_f32 v111, v112, v113
	v_cvt_pk_bf16_f32 v112, v106, v107
	v_cvt_pk_bf16_f32 v113, v108, v109
	global_store_dwordx4 v[122:123], v[110:113], off offset:256 sc1
	v_cvt_pk_bf16_f32 v94, v94, v95
	v_cvt_pk_bf16_f32 v95, v96, v97
	v_or_b32_e32 v110, 16, v154
	v_ashrrev_i32_e32 v111, 31, v110
	v_lshlrev_b64 v[110:111], 13, v[110:111]
	v_lshl_add_u64 v[110:111], s[8:9], 0, v[110:111]
	v_lshl_add_u64 v[110:111], v[110:111], 0, v[124:125]
	v_cvt_pk_bf16_f32 v96, v90, v91
	v_cvt_pk_bf16_f32 v97, v92, v93
	global_store_dwordx4 v[110:111], v[94:97], off offset:256 sc1
	v_cvt_pk_bf16_f32 v62, v62, v63
	v_cvt_pk_bf16_f32 v63, v64, v65
	v_or_b32_e32 v94, 32, v154
	v_ashrrev_i32_e32 v95, 31, v94
	v_cvt_pk_bf16_f32 v65, v60, v61
	v_add_co_u32_e32 v60, vcc, s66, v122
	v_lshlrev_b64 v[94:95], 13, v[94:95]
	v_cvt_pk_bf16_f32 v64, v58, v59
	v_lshl_add_u64 v[58:59], v[122:123], 0, s[10:11]
	v_addc_co_u32_e32 v61, vcc, 0, v123, vcc
	v_cvt_pk_bf16_f32 v46, v46, v47
	v_cvt_pk_bf16_f32 v47, v48, v49
	v_cvt_pk_bf16_f32 v48, v42, v43
	v_cvt_pk_bf16_f32 v49, v44, v45
	v_lshl_add_u64 v[94:95], s[8:9], 0, v[94:95]
	global_store_dwordx4 v[58:59], v[46:49], off offset:256 sc1
	v_lshl_add_u64 v[94:95], v[94:95], 0, v[124:125]
	v_cvt_pk_bf16_f32 v78, v78, v79
	v_add_co_u32_e32 v48, vcc, s67, v122
	v_cvt_pk_bf16_f32 v79, v80, v81
	v_cvt_pk_bf16_f32 v80, v74, v75
	v_cvt_pk_bf16_f32 v81, v76, v77
	v_lshl_add_u64 v[46:47], v[122:123], 0, s[18:19]
	v_addc_co_u32_e32 v49, vcc, 0, v123, vcc
	v_cvt_pk_bf16_f32 v30, v30, v31
	v_cvt_pk_bf16_f32 v31, v32, v33
	v_cvt_pk_bf16_f32 v32, v26, v27
	v_cvt_pk_bf16_f32 v33, v28, v29
	global_store_dwordx4 v[94:95], v[78:81], off offset:256 sc1
	global_store_dwordx4 v[46:47], v[30:33], off offset:256 sc1
	v_cvt_pk_bf16_f32 v14, v14, v15
	v_or_b32_e32 v78, 48, v154
	v_add_co_u32_e32 v32, vcc, s68, v122
	v_ashrrev_i32_e32 v79, 31, v78
	v_lshl_add_u64 v[30:31], v[122:123], 0, s[20:21]
	v_addc_co_u32_e32 v33, vcc, 0, v123, vcc
	v_cvt_pk_bf16_f32 v15, v16, v17
	v_cvt_pk_bf16_f32 v16, v10, v11
	v_cvt_pk_bf16_f32 v17, v12, v13
	v_lshlrev_b64 v[78:79], 13, v[78:79]
	global_store_dwordx4 v[30:31], v[14:17], off offset:256 sc1
	v_lshl_add_u64 v[78:79], s[8:9], 0, v[78:79]
	v_cvt_pk_bf16_f32 v106, v118, v119
	v_add_co_u32_e32 v16, vcc, s69, v122
	v_cvt_pk_bf16_f32 v107, v120, v121
	s_nop 0
	v_addc_co_u32_e32 v17, vcc, 0, v123, vcc
	v_cvt_pk_bf16_f32 v108, v114, v115
	v_cvt_pk_bf16_f32 v109, v116, v117
	v_cvt_pk_bf16_f32 v90, v102, v103
	v_cvt_pk_bf16_f32 v91, v104, v105
	v_cvt_pk_bf16_f32 v92, v98, v99
	v_cvt_pk_bf16_f32 v93, v100, v101
	v_cvt_pk_bf16_f32 v74, v86, v87
	v_cvt_pk_bf16_f32 v75, v88, v89
	v_cvt_pk_bf16_f32 v76, v82, v83
	v_cvt_pk_bf16_f32 v77, v84, v85
	v_lshl_add_u64 v[78:79], v[78:79], 0, v[124:125]
	v_cvt_pk_bf16_f32 v70, v70, v71
	v_cvt_pk_bf16_f32 v71, v72, v73
	v_cvt_pk_bf16_f32 v72, v66, v67
	v_cvt_pk_bf16_f32 v73, v68, v69
	v_cvt_pk_bf16_f32 v42, v54, v55
	v_cvt_pk_bf16_f32 v43, v56, v57
	v_cvt_pk_bf16_f32 v44, v50, v51
	v_cvt_pk_bf16_f32 v45, v52, v53
	v_cvt_pk_bf16_f32 v26, v38, v39
	v_cvt_pk_bf16_f32 v27, v40, v41
	v_cvt_pk_bf16_f32 v28, v34, v35
	v_cvt_pk_bf16_f32 v29, v36, v37
	v_cvt_pk_bf16_f32 v10, v22, v23
	v_cvt_pk_bf16_f32 v11, v24, v25
	v_cvt_pk_bf16_f32 v12, v18, v19
	v_cvt_pk_bf16_f32 v13, v20, v21
	v_lshl_add_u64 v[14:15], v[122:123], 0, s[22:23]
	v_cvt_pk_bf16_f32 v6, v6, v7
	v_cvt_pk_bf16_f32 v7, v8, v9
	v_cvt_pk_bf16_f32 v8, v2, v3
	v_cvt_pk_bf16_f32 v9, v4, v5
	s_andn2_b64 vcc, exec, s[4:5]
	s_mov_b64 s[4:5], -1
	global_store_dwordx4 v[122:123], v[126:129], off sc1
	global_store_dwordx4 v[110:111], v[106:109], off sc1
	global_store_dwordx4 v[94:95], v[90:93], off sc1
	global_store_dwordx4 v[78:79], v[74:77], off sc1
	global_store_dwordx4 v[78:79], v[70:73], off offset:256 sc1
	global_store_dwordx4 v[60:61], v[62:65], off sc1
	global_store_dwordx4 v[48:49], v[42:45], off sc1
	global_store_dwordx4 v[32:33], v[26:29], off sc1
	global_store_dwordx4 v[16:17], v[10:13], off sc1
	global_store_dwordx4 v[14:15], v[6:9], off offset:256 sc1
	s_cbranch_vccnz .LBB0_325
	s_andn2_b64 vcc, exec, s[12:13]
	s_cbranch_vccnz .LBB0_324
	s_barrier
	s_branch .LBB0_324

.LBB0_975:
	v_lshl_add_u32 v150, s46, 8, v152
	v_add_u32_e32 v149, 0xffffc000, v150
	v_ashrrev_i32_e32 v151, 31, v150
	v_cmp_gt_i32_e32 vcc, s56, v150
	v_lshl_or_b32 v148, s66, 8, v154
	v_mov_b32_e32 v160, s10
	v_cndmask_b32_e32 v159, 0, v151, vcc
	v_cndmask_b32_e32 v158, v149, v150, vcc
	v_lshlrev_b64 v[162:163], 12, v[158:159]
	v_mov_b32_e32 v158, s11
	v_mov_b32_e32 v159, s13
	v_mov_b32_e32 v161, s12
	v_cndmask_b32_e32 v165, v158, v159, vcc
	v_cndmask_b32_e32 v164, v160, v161, vcc
	v_ashrrev_i32_e32 v149, 31, v148
	v_lshl_add_u64 v[162:163], v[164:165], 0, v[162:163]
	v_lshlrev_b64 v[148:149], 2, v[148:149]
	v_lshl_add_u64 v[170:171], v[162:163], 0, v[148:149]
	global_load_dwordx4 v[162:165], v[170:171], off
	global_load_dwordx4 v[166:169], v[170:171], off offset:16
	v_lshlrev_b64 v[172:173], 12, v[150:151]
	v_lshl_add_u64 v[172:173], s[8:9], 0, v[172:173]
	v_lshl_add_u64 v[172:173], v[172:173], 0, v[148:149]
	v_add_u32_e32 v151, 0xffffc010, v150
	s_waitcnt vmcnt(0)
	v_pk_add_f32 v[128:129], v[128:129], v[164:165]
	v_pk_add_f32 v[126:127], v[126:127], v[162:163]
	v_pk_add_f32 v[124:125], v[124:125], v[168:169]
	v_pk_add_f32 v[122:123], v[122:123], v[166:167]
	global_store_dwordx4 v[172:173], v[126:129], off sc1
	global_store_dwordx4 v[172:173], v[122:125], off offset:16 sc1
	global_load_dwordx4 v[122:125], v[170:171], off offset:512
	s_nop 0
	global_load_dwordx4 v[126:129], v[170:171], off offset:528
	v_or_b32_e32 v162, 16, v150
	v_ashrrev_i32_e32 v163, 31, v162
	v_cmp_gt_i32_e32 vcc, s56, v162
	s_waitcnt vmcnt(1)
	v_pk_add_f32 v[116:117], v[116:117], v[124:125]
	v_cndmask_b32_e32 v165, 0, v163, vcc
	v_cndmask_b32_e32 v164, v151, v162, vcc
	v_cndmask_b32_e32 v167, v158, v159, vcc
	v_cndmask_b32_e32 v166, v160, v161, vcc
	v_lshlrev_b64 v[164:165], 12, v[164:165]
	v_lshl_add_u64 v[164:165], v[166:167], 0, v[164:165]
	v_pk_add_f32 v[114:115], v[114:115], v[122:123]
	v_lshl_add_u64 v[164:165], v[164:165], 0, v[148:149]
	s_waitcnt vmcnt(0)
	v_pk_add_f32 v[112:113], v[112:113], v[128:129]
	v_pk_add_f32 v[110:111], v[110:111], v[126:127]
	global_store_dwordx4 v[172:173], v[114:117], off offset:512 sc1
	global_store_dwordx4 v[172:173], v[110:113], off offset:528 sc1
	global_load_dwordx4 v[110:113], v[164:165], off
	s_nop 0
	global_load_dwordx4 v[114:117], v[164:165], off offset:16
	v_lshlrev_b64 v[122:123], 12, v[162:163]
	v_lshl_add_u64 v[122:123], s[8:9], 0, v[122:123]
	v_lshl_add_u64 v[122:123], v[122:123], 0, v[148:149]
	s_waitcnt vmcnt(1)
	v_pk_add_f32 v[112:113], v[120:121], v[112:113]
	v_pk_add_f32 v[110:111], v[118:119], v[110:111]
	s_waitcnt vmcnt(0)
	v_pk_add_f32 v[108:109], v[108:109], v[116:117]
	v_pk_add_f32 v[106:107], v[106:107], v[114:115]
	global_store_dwordx4 v[122:123], v[110:113], off sc1
	global_store_dwordx4 v[122:123], v[106:109], off offset:16 sc1
	global_load_dwordx4 v[106:109], v[164:165], off offset:512
	s_nop 0
	global_load_dwordx4 v[110:113], v[164:165], off offset:528
	v_or_b32_e32 v114, 32, v150
	v_add_u32_e32 v116, 0xffffc020, v150
	v_ashrrev_i32_e32 v115, 31, v114
	v_cmp_gt_i32_e32 vcc, s56, v114
	s_waitcnt vmcnt(1)
	v_pk_add_f32 v[100:101], v[100:101], v[108:109]
	v_cndmask_b32_e32 v117, 0, v115, vcc
	v_cndmask_b32_e32 v116, v116, v114, vcc
	v_cndmask_b32_e32 v119, v158, v159, vcc
	v_cndmask_b32_e32 v118, v160, v161, vcc
	v_lshlrev_b64 v[116:117], 12, v[116:117]
	v_lshl_add_u64 v[116:117], v[118:119], 0, v[116:117]
	v_pk_add_f32 v[98:99], v[98:99], v[106:107]
	v_lshl_add_u64 v[116:117], v[116:117], 0, v[148:149]
	s_waitcnt vmcnt(0)
	v_pk_add_f32 v[96:97], v[96:97], v[112:113]
	v_pk_add_f32 v[94:95], v[94:95], v[110:111]
	global_store_dwordx4 v[122:123], v[98:101], off offset:512 sc1
	global_store_dwordx4 v[122:123], v[94:97], off offset:528 sc1
	global_load_dwordx4 v[94:97], v[116:117], off
	s_nop 0
	global_load_dwordx4 v[98:101], v[116:117], off offset:16
	v_lshlrev_b64 v[106:107], 12, v[114:115]
	v_lshl_add_u64 v[106:107], s[8:9], 0, v[106:107]
	v_lshl_add_u64 v[106:107], v[106:107], 0, v[148:149]
	s_waitcnt vmcnt(1)
	v_pk_add_f32 v[96:97], v[104:105], v[96:97]
	v_pk_add_f32 v[94:95], v[102:103], v[94:95]
	s_waitcnt vmcnt(0)
	v_pk_add_f32 v[92:93], v[92:93], v[100:101]
	v_pk_add_f32 v[90:91], v[90:91], v[98:99]
	global_store_dwordx4 v[106:107], v[94:97], off sc1
	global_store_dwordx4 v[106:107], v[90:93], off offset:16 sc1
	global_load_dwordx4 v[90:93], v[116:117], off offset:512
	s_nop 0
	global_load_dwordx4 v[94:97], v[116:117], off offset:528
	v_or_b32_e32 v98, 48, v150
	v_add_u32_e32 v100, 0xffffc030, v150
	v_ashrrev_i32_e32 v99, 31, v98
	v_cmp_gt_i32_e32 vcc, s56, v98
	s_waitcnt vmcnt(1)
	v_pk_add_f32 v[84:85], v[84:85], v[92:93]
	v_cndmask_b32_e32 v101, 0, v99, vcc
	v_cndmask_b32_e32 v100, v100, v98, vcc
	v_cndmask_b32_e32 v103, v158, v159, vcc
	v_cndmask_b32_e32 v102, v160, v161, vcc
	v_lshlrev_b64 v[100:101], 12, v[100:101]
	v_lshl_add_u64 v[100:101], v[102:103], 0, v[100:101]
	v_pk_add_f32 v[82:83], v[82:83], v[90:91]
	v_lshl_add_u64 v[100:101], v[100:101], 0, v[148:149]
	s_waitcnt vmcnt(0)
	v_pk_add_f32 v[80:81], v[80:81], v[96:97]
	v_pk_add_f32 v[78:79], v[78:79], v[94:95]
	global_store_dwordx4 v[106:107], v[82:85], off offset:512 sc1
	global_store_dwordx4 v[106:107], v[78:81], off offset:528 sc1
	global_load_dwordx4 v[78:81], v[100:101], off
	s_nop 0
	global_load_dwordx4 v[82:85], v[100:101], off offset:16
	v_lshlrev_b64 v[90:91], 12, v[98:99]
	v_lshl_add_u64 v[90:91], s[8:9], 0, v[90:91]
	v_lshl_add_u64 v[90:91], v[90:91], 0, v[148:149]
	v_cmp_gt_i32_e32 vcc, s62, v150
	s_waitcnt vmcnt(1)
	v_pk_add_f32 v[80:81], v[88:89], v[80:81]
	v_pk_add_f32 v[78:79], v[86:87], v[78:79]
	s_waitcnt vmcnt(0)
	v_pk_add_f32 v[76:77], v[76:77], v[84:85]
	v_pk_add_f32 v[74:75], v[74:75], v[82:83]
	global_store_dwordx4 v[90:91], v[78:81], off sc1
	global_store_dwordx4 v[90:91], v[74:77], off offset:16 sc1
	global_load_dwordx4 v[74:77], v[100:101], off offset:512
	s_nop 0
	global_load_dwordx4 v[78:81], v[100:101], off offset:528
	v_add_u32_e32 v82, 0x80, v150
	v_add_u32_e32 v84, 0xffffc080, v150
	v_ashrrev_i32_e32 v83, 31, v82
	v_cndmask_b32_e32 v85, 0, v83, vcc
	v_cndmask_b32_e32 v84, v84, v82, vcc
	v_cndmask_b32_e32 v87, v158, v159, vcc
	v_cndmask_b32_e32 v86, v160, v161, vcc
	v_lshlrev_b64 v[84:85], 12, v[84:85]
	v_lshl_add_u64 v[84:85], v[86:87], 0, v[84:85]
	v_lshl_add_u64 v[84:85], v[84:85], 0, v[148:149]
	v_cmp_gt_i32_e32 vcc, s63, v150
	s_waitcnt vmcnt(1)
	v_pk_add_f32 v[72:73], v[72:73], v[76:77]
	v_pk_add_f32 v[70:71], v[70:71], v[74:75]
	s_waitcnt vmcnt(0)
	v_pk_add_f32 v[68:69], v[68:69], v[80:81]
	v_pk_add_f32 v[66:67], v[66:67], v[78:79]
	global_store_dwordx4 v[90:91], v[70:73], off offset:512 sc1
	global_store_dwordx4 v[90:91], v[66:69], off offset:528 sc1
	global_load_dwordx4 v[66:69], v[84:85], off
	s_nop 0
	global_load_dwordx4 v[70:73], v[84:85], off offset:16
	v_lshlrev_b64 v[74:75], 12, v[82:83]
	v_lshl_add_u64 v[74:75], s[8:9], 0, v[74:75]
	v_lshl_add_u64 v[74:75], v[74:75], 0, v[148:149]
	s_waitcnt vmcnt(1)
	v_pk_add_f32 v[64:65], v[64:65], v[68:69]
	v_pk_add_f32 v[62:63], v[62:63], v[66:67]
	s_waitcnt vmcnt(0)
	v_pk_add_f32 v[60:61], v[60:61], v[72:73]
	v_pk_add_f32 v[58:59], v[58:59], v[70:71]
	global_store_dwordx4 v[74:75], v[62:65], off sc1
	global_store_dwordx4 v[74:75], v[58:61], off offset:16 sc1
	global_load_dwordx4 v[58:61], v[84:85], off offset:512
	s_nop 0
	global_load_dwordx4 v[62:65], v[84:85], off offset:528
	v_add_u32_e32 v66, 0x90, v150
	v_add_u32_e32 v68, 0xffffc090, v150
	v_ashrrev_i32_e32 v67, 31, v66
	v_cndmask_b32_e32 v69, 0, v67, vcc
	v_cndmask_b32_e32 v68, v68, v66, vcc
	v_cndmask_b32_e32 v71, v158, v159, vcc
	v_cndmask_b32_e32 v70, v160, v161, vcc
	v_lshlrev_b64 v[68:69], 12, v[68:69]
	v_lshl_add_u64 v[68:69], v[70:71], 0, v[68:69]
	v_lshl_add_u64 v[68:69], v[68:69], 0, v[148:149]
	v_cmp_gt_i32_e32 vcc, s64, v150
	s_waitcnt vmcnt(1)
	v_pk_add_f32 v[52:53], v[52:53], v[60:61]
	v_pk_add_f32 v[50:51], v[50:51], v[58:59]
	s_waitcnt vmcnt(0)
	v_pk_add_f32 v[48:49], v[48:49], v[64:65]
	v_pk_add_f32 v[46:47], v[46:47], v[62:63]
	global_store_dwordx4 v[74:75], v[50:53], off offset:512 sc1
	global_store_dwordx4 v[74:75], v[46:49], off offset:528 sc1
	global_load_dwordx4 v[46:49], v[68:69], off
	s_nop 0
	global_load_dwordx4 v[50:53], v[68:69], off offset:16
	v_lshlrev_b64 v[58:59], 12, v[66:67]
	v_lshl_add_u64 v[58:59], s[8:9], 0, v[58:59]
	v_lshl_add_u64 v[58:59], v[58:59], 0, v[148:149]
	s_waitcnt vmcnt(1)
	v_pk_add_f32 v[48:49], v[56:57], v[48:49]
	v_pk_add_f32 v[46:47], v[54:55], v[46:47]
	s_waitcnt vmcnt(0)
	v_pk_add_f32 v[44:45], v[44:45], v[52:53]
	v_pk_add_f32 v[42:43], v[42:43], v[50:51]
	global_store_dwordx4 v[58:59], v[46:49], off sc1
	global_store_dwordx4 v[58:59], v[42:45], off offset:16 sc1
	global_load_dwordx4 v[42:45], v[68:69], off offset:512
	s_nop 0
	global_load_dwordx4 v[46:49], v[68:69], off offset:528
	v_add_u32_e32 v50, 0xa0, v150
	v_add_u32_e32 v52, 0xffffc0a0, v150
	v_ashrrev_i32_e32 v51, 31, v50
	v_cndmask_b32_e32 v53, 0, v51, vcc
	v_cndmask_b32_e32 v52, v52, v50, vcc
	v_cndmask_b32_e32 v55, v158, v159, vcc
	v_cndmask_b32_e32 v54, v160, v161, vcc
	v_lshlrev_b64 v[52:53], 12, v[52:53]
	v_lshl_add_u64 v[52:53], v[54:55], 0, v[52:53]
	v_lshl_add_u64 v[52:53], v[52:53], 0, v[148:149]
	v_cmp_gt_i32_e32 vcc, s65, v150
	s_waitcnt vmcnt(1)
	v_pk_add_f32 v[36:37], v[36:37], v[44:45]
	v_pk_add_f32 v[34:35], v[34:35], v[42:43]
	s_waitcnt vmcnt(0)
	v_pk_add_f32 v[32:33], v[32:33], v[48:49]
	v_pk_add_f32 v[30:31], v[30:31], v[46:47]
	global_store_dwordx4 v[58:59], v[34:37], off offset:512 sc1
	global_store_dwordx4 v[58:59], v[30:33], off offset:528 sc1
	global_load_dwordx4 v[30:33], v[52:53], off
	s_nop 0
	global_load_dwordx4 v[34:37], v[52:53], off offset:16
	v_lshlrev_b64 v[42:43], 12, v[50:51]
	v_lshl_add_u64 v[42:43], s[8:9], 0, v[42:43]
	v_lshl_add_u64 v[42:43], v[42:43], 0, v[148:149]
	s_waitcnt vmcnt(1)
	v_pk_add_f32 v[32:33], v[40:41], v[32:33]
	v_pk_add_f32 v[30:31], v[38:39], v[30:31]
	s_waitcnt vmcnt(0)
	v_pk_add_f32 v[28:29], v[28:29], v[36:37]
	v_pk_add_f32 v[26:27], v[26:27], v[34:35]
	global_store_dwordx4 v[42:43], v[30:33], off sc1
	global_store_dwordx4 v[42:43], v[26:29], off offset:16 sc1
	global_load_dwordx4 v[26:29], v[52:53], off offset:512
	s_nop 0
	global_load_dwordx4 v[30:33], v[52:53], off offset:528
	v_add_u32_e32 v34, 0xb0, v150
	v_add_u32_e32 v36, 0xffffc0b0, v150
	v_ashrrev_i32_e32 v35, 31, v34
	v_cndmask_b32_e32 v37, 0, v35, vcc
	v_cndmask_b32_e32 v36, v36, v34, vcc
	v_cndmask_b32_e32 v39, v158, v159, vcc
	v_cndmask_b32_e32 v38, v160, v161, vcc
	v_lshlrev_b64 v[36:37], 12, v[36:37]
	v_lshl_add_u64 v[36:37], v[38:39], 0, v[36:37]
	v_lshl_add_u64 v[36:37], v[36:37], 0, v[148:149]
	s_andn2_b64 vcc, exec, s[4:5]
	s_mov_b64 s[4:5], -1
	s_waitcnt vmcnt(1)
	v_pk_add_f32 v[20:21], v[20:21], v[28:29]
	v_pk_add_f32 v[18:19], v[18:19], v[26:27]
	s_waitcnt vmcnt(0)
	v_pk_add_f32 v[16:17], v[16:17], v[32:33]
	v_pk_add_f32 v[14:15], v[14:15], v[30:31]
	global_store_dwordx4 v[42:43], v[18:21], off offset:512 sc1
	global_store_dwordx4 v[42:43], v[14:17], off offset:528 sc1
	global_load_dwordx4 v[14:17], v[36:37], off
	s_nop 0
	global_load_dwordx4 v[18:21], v[36:37], off offset:16
	v_lshlrev_b64 v[26:27], 12, v[34:35]
	v_lshl_add_u64 v[26:27], s[8:9], 0, v[26:27]
	v_lshl_add_u64 v[26:27], v[26:27], 0, v[148:149]
	s_waitcnt vmcnt(1)
	v_pk_add_f32 v[16:17], v[24:25], v[16:17]
	v_pk_add_f32 v[14:15], v[22:23], v[14:15]
	s_waitcnt vmcnt(0)
	v_pk_add_f32 v[12:13], v[12:13], v[20:21]
	v_pk_add_f32 v[10:11], v[10:11], v[18:19]
	global_store_dwordx4 v[26:27], v[14:17], off sc1
	global_store_dwordx4 v[26:27], v[10:13], off offset:16 sc1
	global_load_dwordx4 v[10:13], v[36:37], off offset:512
	s_nop 0
	global_load_dwordx4 v[14:17], v[36:37], off offset:528
	s_waitcnt vmcnt(1)
	v_pk_add_f32 v[8:9], v[8:9], v[12:13]
	v_pk_add_f32 v[6:7], v[6:7], v[10:11]
	s_waitcnt vmcnt(0)
	v_pk_add_f32 v[4:5], v[4:5], v[16:17]
	v_pk_add_f32 v[2:3], v[2:3], v[14:15]
	global_store_dwordx4 v[26:27], v[6:9], off offset:512 sc1
	global_store_dwordx4 v[26:27], v[2:5], off offset:528 sc1
	s_cbranch_vccnz .LBB0_964
	s_andn2_b64 vcc, exec, s[14:15]
	s_cbranch_vccnz .LBB0_963
	s_barrier
	s_branch .LBB0_963

.LBB0_982:
	v_add_co_u32_e32 v58, vcc, 0x900000, v18
	s_nop 1
	v_addc_co_u32_e32 v59, vcc, 0, v19, vcc
	v_add_co_u32_e32 v60, vcc, 0x26e13000, v16
	s_nop 1
	v_addc_co_u32_e32 v61, vcc, 0, v17, vcc
	global_load_dwordx4 v[26:29], v[58:59], off
	global_load_dwordx4 v[176:179], v[60:61], off
	global_load_dwordx4 v[30:33], v[58:59], off offset:64
	global_load_dwordx4 v[180:183], v[60:61], off offset:64
	global_load_dwordx4 v[34:37], v[58:59], off offset:128
	global_load_dwordx4 v[184:187], v[60:61], off offset:128
	global_load_dwordx4 v[38:41], v[58:59], off offset:192
	global_load_dwordx4 v[188:191], v[60:61], off offset:192
	global_load_dwordx4 v[42:45], v[58:59], off offset:256
	global_load_dwordx4 v[192:195], v[60:61], off offset:256
	global_load_dwordx4 v[46:49], v[58:59], off offset:320
	global_load_dwordx4 v[196:199], v[60:61], off offset:320
	global_load_dwordx4 v[50:53], v[58:59], off offset:384
	global_load_dwordx4 v[200:203], v[60:61], off offset:384
	global_load_dwordx4 v[54:57], v[58:59], off offset:448
	global_load_dwordx4 v[204:207], v[60:61], off offset:448
	global_load_dwordx4 v[132:135], v[58:59], off offset:512
	global_load_dwordx4 v[208:211], v[60:61], off offset:512
	global_load_dwordx4 v[136:139], v[58:59], off offset:576
	global_load_dwordx4 v[212:215], v[60:61], off offset:576
	global_load_dwordx4 v[140:143], v[58:59], off offset:640
	global_load_dwordx4 v[216:219], v[60:61], off offset:640
	global_load_dwordx4 v[148:151], v[58:59], off offset:704
	global_load_dwordx4 v[220:223], v[60:61], off offset:704
	global_load_dwordx4 v[152:155], v[58:59], off offset:768
	global_load_dwordx4 v[224:227], v[60:61], off offset:768
	global_load_dwordx4 v[156:159], v[58:59], off offset:832
	global_load_dwordx4 v[228:231], v[60:61], off offset:832
	global_load_dwordx4 v[168:171], v[58:59], off offset:896
	global_load_dwordx4 v[232:235], v[60:61], off offset:896
	global_load_dwordx4 v[172:175], v[58:59], off offset:960
	global_load_dwordx4 v[236:239], v[60:61], off offset:960
	s_waitcnt vmcnt(30)
	v_mfma_f32_16x16x32_bf16 v[2:5], v[26:29], v[176:179], v[2:5]
	global_load_dwordx4 v[26:29], v[58:59], off offset:1024
	global_load_dwordx4 v[176:179], v[60:61], off offset:1024
	s_waitcnt vmcnt(30)
	v_mfma_f32_16x16x32_bf16 v[2:5], v[30:33], v[180:183], v[2:5]
	global_load_dwordx4 v[30:33], v[58:59], off offset:1088
	global_load_dwordx4 v[180:183], v[60:61], off offset:1088
	s_waitcnt vmcnt(30)
	v_mfma_f32_16x16x32_bf16 v[2:5], v[34:37], v[184:187], v[2:5]
	global_load_dwordx4 v[34:37], v[58:59], off offset:1152
	global_load_dwordx4 v[184:187], v[60:61], off offset:1152
	s_waitcnt vmcnt(30)
	v_mfma_f32_16x16x32_bf16 v[2:5], v[38:41], v[188:191], v[2:5]
	global_load_dwordx4 v[38:41], v[58:59], off offset:1216
	global_load_dwordx4 v[188:191], v[60:61], off offset:1216
	s_waitcnt vmcnt(30)
	v_mfma_f32_16x16x32_bf16 v[2:5], v[42:45], v[192:195], v[2:5]
	global_load_dwordx4 v[42:45], v[58:59], off offset:1280
	global_load_dwordx4 v[192:195], v[60:61], off offset:1280
	s_waitcnt vmcnt(30)
	v_mfma_f32_16x16x32_bf16 v[2:5], v[46:49], v[196:199], v[2:5]
	global_load_dwordx4 v[46:49], v[58:59], off offset:1344
	global_load_dwordx4 v[196:199], v[60:61], off offset:1344
	s_waitcnt vmcnt(30)
	v_mfma_f32_16x16x32_bf16 v[2:5], v[50:53], v[200:203], v[2:5]
	global_load_dwordx4 v[50:53], v[58:59], off offset:1408
	global_load_dwordx4 v[200:203], v[60:61], off offset:1408
	s_waitcnt vmcnt(30)
	v_mfma_f32_16x16x32_bf16 v[2:5], v[54:57], v[204:207], v[2:5]
	global_load_dwordx4 v[54:57], v[58:59], off offset:1472
	global_load_dwordx4 v[204:207], v[60:61], off offset:1472
	s_waitcnt vmcnt(30)
	v_mfma_f32_16x16x32_bf16 v[2:5], v[132:135], v[208:211], v[2:5]
	global_load_dwordx4 v[132:135], v[58:59], off offset:1536
	global_load_dwordx4 v[208:211], v[60:61], off offset:1536
	s_waitcnt vmcnt(30)
	v_mfma_f32_16x16x32_bf16 v[2:5], v[136:139], v[212:215], v[2:5]
	global_load_dwordx4 v[136:139], v[58:59], off offset:1600
	global_load_dwordx4 v[212:215], v[60:61], off offset:1600
	s_waitcnt vmcnt(30)
	v_mfma_f32_16x16x32_bf16 v[2:5], v[140:143], v[216:219], v[2:5]
	global_load_dwordx4 v[140:143], v[58:59], off offset:1664
	global_load_dwordx4 v[216:219], v[60:61], off offset:1664
	s_waitcnt vmcnt(30)
	v_mfma_f32_16x16x32_bf16 v[2:5], v[148:151], v[220:223], v[2:5]
	global_load_dwordx4 v[148:151], v[58:59], off offset:1728
	global_load_dwordx4 v[220:223], v[60:61], off offset:1728
	s_waitcnt vmcnt(30)
	v_mfma_f32_16x16x32_bf16 v[2:5], v[152:155], v[224:227], v[2:5]
	global_load_dwordx4 v[152:155], v[58:59], off offset:1792
	global_load_dwordx4 v[224:227], v[60:61], off offset:1792
	s_waitcnt vmcnt(30)
	v_mfma_f32_16x16x32_bf16 v[2:5], v[156:159], v[228:231], v[2:5]
	global_load_dwordx4 v[156:159], v[58:59], off offset:1856
	global_load_dwordx4 v[228:231], v[60:61], off offset:1856
	s_waitcnt vmcnt(30)
	v_mfma_f32_16x16x32_bf16 v[2:5], v[168:171], v[232:235], v[2:5]
	global_load_dwordx4 v[168:171], v[58:59], off offset:1920
	global_load_dwordx4 v[232:235], v[60:61], off offset:1920
	s_waitcnt vmcnt(30)
	v_mfma_f32_16x16x32_bf16 v[2:5], v[172:175], v[236:239], v[2:5]
	global_load_dwordx4 v[172:175], v[58:59], off offset:1984
	global_load_dwordx4 v[236:239], v[60:61], off offset:1984
	s_waitcnt vmcnt(30)
	v_mfma_f32_16x16x32_bf16 v[2:5], v[26:29], v[176:179], v[2:5]
	s_waitcnt vmcnt(28)
	v_mfma_f32_16x16x32_bf16 v[2:5], v[30:33], v[180:183], v[2:5]
	s_waitcnt vmcnt(26)
	v_mfma_f32_16x16x32_bf16 v[2:5], v[34:37], v[184:187], v[2:5]
	s_waitcnt vmcnt(24)
	v_mfma_f32_16x16x32_bf16 v[2:5], v[38:41], v[188:191], v[2:5]
	s_waitcnt vmcnt(22)
	v_mfma_f32_16x16x32_bf16 v[2:5], v[42:45], v[192:195], v[2:5]
	s_waitcnt vmcnt(20)
	v_mfma_f32_16x16x32_bf16 v[2:5], v[46:49], v[196:199], v[2:5]
	s_waitcnt vmcnt(18)
	v_mfma_f32_16x16x32_bf16 v[2:5], v[50:53], v[200:203], v[2:5]
	s_waitcnt vmcnt(16)
	v_mfma_f32_16x16x32_bf16 v[2:5], v[54:57], v[204:207], v[2:5]
	s_waitcnt vmcnt(14)
	v_mfma_f32_16x16x32_bf16 v[2:5], v[132:135], v[208:211], v[2:5]
	s_waitcnt vmcnt(12)
	v_mfma_f32_16x16x32_bf16 v[2:5], v[136:139], v[212:215], v[2:5]
	s_waitcnt vmcnt(10)
	v_mfma_f32_16x16x32_bf16 v[2:5], v[140:143], v[216:219], v[2:5]
	s_waitcnt vmcnt(8)
	v_mfma_f32_16x16x32_bf16 v[2:5], v[148:151], v[220:223], v[2:5]
	s_waitcnt vmcnt(6)
	v_mfma_f32_16x16x32_bf16 v[2:5], v[152:155], v[224:227], v[2:5]
	s_waitcnt vmcnt(4)
	v_mfma_f32_16x16x32_bf16 v[2:5], v[156:159], v[228:231], v[2:5]
	s_waitcnt vmcnt(2)
	v_mfma_f32_16x16x32_bf16 v[2:5], v[168:171], v[232:235], v[2:5]
	s_waitcnt vmcnt(0)
	v_mfma_f32_16x16x32_bf16 v[2:5], v[172:175], v[236:239], v[2:5]
	s_movk_i32 s4, 0x800
	s_nop 1
	v_lshl_or_b32 v18, s8, 4, v20
	v_ashrrev_i32_e32 v19, 31, v18
	v_lshlrev_b64 v[18:19], 2, v[18:19]
	v_lshl_add_u64 v[22:23], v[10:11], 0, v[18:19]
	global_load_dwordx4 v[22:25], v[22:23], off
	s_add_i32 s8, s8, s90
	s_cmp_gt_i32 s8, 63
	v_lshl_add_u64 v[18:19], v[8:9], 0, v[18:19]
	v_add_u32_e32 v14, s3, v14
	s_waitcnt vmcnt(0)
	v_pk_add_f32 v[4:5], v[4:5], v[24:25]
	v_pk_add_f32 v[2:3], v[2:3], v[22:23]
	global_store_dwordx4 v[18:19], v[2:5], off sc1
	s_cbranch_scc0 .LBB0_981

.LBB0_1103:
	v_lshl_add_u32 v154, s26, 8, v148
	v_lshl_or_b32 v156, s69, 8, v150
	v_ashrrev_i32_e32 v155, 31, v154
	v_cvt_pk_bf16_f32 v126, v126, v127
	v_cvt_pk_bf16_f32 v127, v128, v129
	v_cvt_pk_bf16_f32 v128, v122, v123
	v_lshlrev_b64 v[122:123], 12, v[154:155]
	v_ashrrev_i32_e32 v157, 31, v156
	v_cvt_pk_bf16_f32 v129, v124, v125
	v_lshl_add_u64 v[122:123], s[8:9], 0, v[122:123]
	v_lshlrev_b64 v[124:125], 1, v[156:157]
	v_lshl_add_u64 v[122:123], v[122:123], 0, v[124:125]
	v_cvt_pk_bf16_f32 v110, v110, v111
	v_cvt_pk_bf16_f32 v111, v112, v113
	v_cvt_pk_bf16_f32 v112, v106, v107
	v_cvt_pk_bf16_f32 v113, v108, v109
	global_store_dwordx4 v[122:123], v[110:113], off offset:256 sc1
	v_cvt_pk_bf16_f32 v94, v94, v95
	v_cvt_pk_bf16_f32 v95, v96, v97
	v_or_b32_e32 v110, 16, v154
	v_ashrrev_i32_e32 v111, 31, v110
	v_lshlrev_b64 v[110:111], 12, v[110:111]
	v_lshl_add_u64 v[110:111], s[8:9], 0, v[110:111]
	v_lshl_add_u64 v[110:111], v[110:111], 0, v[124:125]
	v_cvt_pk_bf16_f32 v96, v90, v91
	v_cvt_pk_bf16_f32 v97, v92, v93
	global_store_dwordx4 v[110:111], v[94:97], off offset:256 sc1
	v_cvt_pk_bf16_f32 v62, v62, v63
	v_cvt_pk_bf16_f32 v63, v64, v65
	v_or_b32_e32 v94, 32, v154
	v_ashrrev_i32_e32 v95, 31, v94
	v_cvt_pk_bf16_f32 v65, v60, v61
	v_add_co_u32_e32 v60, vcc, s65, v122
	v_lshlrev_b64 v[94:95], 12, v[94:95]
	v_cvt_pk_bf16_f32 v64, v58, v59
	v_lshl_add_u64 v[58:59], v[122:123], 0, s[16:17]
	v_addc_co_u32_e32 v61, vcc, 0, v123, vcc
	v_cvt_pk_bf16_f32 v46, v46, v47
	v_cvt_pk_bf16_f32 v47, v48, v49
	v_cvt_pk_bf16_f32 v48, v42, v43
	v_cvt_pk_bf16_f32 v49, v44, v45
	v_lshl_add_u64 v[94:95], s[8:9], 0, v[94:95]
	global_store_dwordx4 v[58:59], v[46:49], off offset:256 sc1
	v_lshl_add_u64 v[94:95], v[94:95], 0, v[124:125]
	v_cvt_pk_bf16_f32 v78, v78, v79
	v_add_co_u32_e32 v48, vcc, s66, v122
	v_cvt_pk_bf16_f32 v79, v80, v81
	v_cvt_pk_bf16_f32 v80, v74, v75
	v_cvt_pk_bf16_f32 v81, v76, v77
	v_lshl_add_u64 v[46:47], v[122:123], 0, s[18:19]
	v_addc_co_u32_e32 v49, vcc, 0, v123, vcc
	v_cvt_pk_bf16_f32 v30, v30, v31
	v_cvt_pk_bf16_f32 v31, v32, v33
	v_cvt_pk_bf16_f32 v32, v26, v27
	v_cvt_pk_bf16_f32 v33, v28, v29
	global_store_dwordx4 v[94:95], v[78:81], off offset:256 sc1
	global_store_dwordx4 v[46:47], v[30:33], off offset:256 sc1
	v_cvt_pk_bf16_f32 v14, v14, v15
	v_or_b32_e32 v78, 48, v154
	v_add_co_u32_e32 v32, vcc, s67, v122
	v_ashrrev_i32_e32 v79, 31, v78
	v_lshl_add_u64 v[30:31], v[122:123], 0, s[20:21]
	v_addc_co_u32_e32 v33, vcc, 0, v123, vcc
	v_cvt_pk_bf16_f32 v15, v16, v17
	v_cvt_pk_bf16_f32 v16, v10, v11
	v_cvt_pk_bf16_f32 v17, v12, v13
	v_lshlrev_b64 v[78:79], 12, v[78:79]
	global_store_dwordx4 v[30:31], v[14:17], off offset:256 sc1
	v_lshl_add_u64 v[78:79], s[8:9], 0, v[78:79]
	v_cvt_pk_bf16_f32 v106, v118, v119
	v_add_co_u32_e32 v16, vcc, s68, v122
	v_cvt_pk_bf16_f32 v107, v120, v121
	s_nop 0
	v_addc_co_u32_e32 v17, vcc, 0, v123, vcc
	v_cvt_pk_bf16_f32 v108, v114, v115
	v_cvt_pk_bf16_f32 v109, v116, v117
	v_cvt_pk_bf16_f32 v90, v102, v103
	v_cvt_pk_bf16_f32 v91, v104, v105
	v_cvt_pk_bf16_f32 v92, v98, v99
	v_cvt_pk_bf16_f32 v93, v100, v101
	v_cvt_pk_bf16_f32 v74, v86, v87
	v_cvt_pk_bf16_f32 v75, v88, v89
	v_cvt_pk_bf16_f32 v76, v82, v83
	v_cvt_pk_bf16_f32 v77, v84, v85
	v_lshl_add_u64 v[78:79], v[78:79], 0, v[124:125]
	v_cvt_pk_bf16_f32 v70, v70, v71
	v_cvt_pk_bf16_f32 v71, v72, v73
	v_cvt_pk_bf16_f32 v72, v66, v67
	v_cvt_pk_bf16_f32 v73, v68, v69
	v_cvt_pk_bf16_f32 v42, v54, v55
	v_cvt_pk_bf16_f32 v43, v56, v57
	v_cvt_pk_bf16_f32 v44, v50, v51
	v_cvt_pk_bf16_f32 v45, v52, v53
	v_cvt_pk_bf16_f32 v26, v38, v39
	v_cvt_pk_bf16_f32 v27, v40, v41
	v_cvt_pk_bf16_f32 v28, v34, v35
	v_cvt_pk_bf16_f32 v29, v36, v37
	v_cvt_pk_bf16_f32 v10, v22, v23
	v_cvt_pk_bf16_f32 v11, v24, v25
	v_cvt_pk_bf16_f32 v12, v18, v19
	v_cvt_pk_bf16_f32 v13, v20, v21
	v_lshl_add_u64 v[14:15], v[122:123], 0, s[22:23]
	v_cvt_pk_bf16_f32 v6, v6, v7
	v_cvt_pk_bf16_f32 v7, v8, v9
	v_cvt_pk_bf16_f32 v8, v2, v3
	v_cvt_pk_bf16_f32 v9, v4, v5
	s_andn2_b64 vcc, exec, s[4:5]
	s_mov_b64 s[4:5], -1
	global_store_dwordx4 v[122:123], v[126:129], off sc1
	global_store_dwordx4 v[110:111], v[106:109], off sc1
	global_store_dwordx4 v[94:95], v[90:93], off sc1
	global_store_dwordx4 v[78:79], v[74:77], off sc1
	global_store_dwordx4 v[78:79], v[70:73], off offset:256 sc1
	global_store_dwordx4 v[60:61], v[62:65], off sc1
	global_store_dwordx4 v[48:49], v[42:45], off sc1
	global_store_dwordx4 v[32:33], v[26:29], off sc1
	global_store_dwordx4 v[16:17], v[10:13], off sc1
	global_store_dwordx4 v[14:15], v[6:9], off offset:256 sc1
	s_cbranch_vccnz .LBB0_1096
	s_andn2_b64 vcc, exec, s[10:11]
	s_cbranch_vccnz .LBB0_1095
	s_barrier
	s_branch .LBB0_1095

.LBB0_1424:
	v_lshl_add_u32 v150, s6, 8, v156
	v_ashrrev_i32_e32 v151, 31, v150
	v_lshl_or_b32 v148, s7, 8, v158
	v_lshlrev_b64 v[152:153], 5, v[150:151]
	v_mad_i64_i32 v[164:165], s[6:7], v150, s63, 0
	v_cmp_gt_i32_e32 vcc, s64, v148
	v_lshl_add_u64 v[154:155], s[12:13], 0, v[152:153]
	v_lshl_add_u64 v[152:153], s[10:11], 0, v[164:165]
	v_ashrrev_i32_e32 v149, 31, v148
	s_and_saveexec_b64 s[6:7], vcc
	s_cbranch_execz .LBB0_1426
	global_load_dwordx4 v[164:167], v[154:155], off
	global_load_dwordx4 v[168:171], v[154:155], off offset:16
	s_waitcnt vmcnt(0)
	v_mov_b32_e32 v172, v164
	v_mov_b32_e32 v173, v168
	v_mov_b32_e32 v168, v165
	v_mov_b32_e32 v164, v166
	v_mov_b32_e32 v165, v170
	v_mov_b32_e32 v170, v167
	v_pk_add_f32 v[166:167], v[172:173], v[168:169]
	v_pk_add_f32 v[164:165], v[164:165], v[170:171]
	s_nop 0
	v_pk_add_f32 v[164:165], v[166:167], v[164:165]
	s_nop 0
	v_add_f32_e32 v151, v164, v165
	v_fmamk_f32 v151, v151, 0x3a800000, v162
	v_rsq_f32_e32 v164, v151
	s_nop 0
	v_pk_mul_f32 v[128:129], v[128:129], v[164:165] op_sel_hi:[1,0]
	v_pk_mul_f32 v[126:127], v[126:127], v[164:165] op_sel_hi:[1,0]
	v_pk_mul_f32 v[166:167], v[124:125], v[164:165] op_sel_hi:[1,0]
	v_pk_mul_f32 v[124:125], v[122:123], v[164:165] op_sel_hi:[1,0]
	v_cvt_pk_bf16_f32 v122, v126, v127
	v_cvt_pk_bf16_f32 v123, v128, v129
	v_cvt_pk_bf16_f32 v124, v124, v125
	v_cvt_pk_bf16_f32 v125, v166, v167
	v_lshl_add_u64 v[126:127], v[148:149], 1, v[152:153]
	global_store_dwordx4 v[126:127], v[122:125], off sc1
.LBB0_1426:
	s_or_b64 exec, exec, s[6:7]
	s_nop 0
	v_or_b32_e32 v122, 0x80, v148
	v_cmp_gt_i32_e64 s[6:7], s64, v122
	s_and_saveexec_b64 s[50:51], s[6:7]
	s_cbranch_execz .LBB0_1428
	global_load_dwordx4 v[122:125], v[154:155], off
	global_load_dwordx4 v[126:129], v[154:155], off offset:16
	s_waitcnt vmcnt(0)
	v_mov_b32_e32 v154, v122
	v_mov_b32_e32 v155, v126
	v_mov_b32_e32 v126, v123
	v_mov_b32_e32 v122, v124
	v_mov_b32_e32 v123, v128
	v_mov_b32_e32 v128, v125
	v_pk_add_f32 v[124:125], v[154:155], v[126:127]
	v_pk_add_f32 v[122:123], v[122:123], v[128:129]
	s_nop 0
	v_pk_add_f32 v[122:123], v[124:125], v[122:123]
	s_nop 0
	v_add_f32_e32 v122, v122, v123
	v_fmamk_f32 v122, v122, 0x3a800000, v162
	v_rsq_f32_e32 v122, v122
	s_nop 0
	v_pk_mul_f32 v[120:121], v[120:121], v[122:123] op_sel_hi:[1,0]
	v_pk_mul_f32 v[118:119], v[118:119], v[122:123] op_sel_hi:[1,0]
	v_pk_mul_f32 v[124:125], v[116:117], v[122:123] op_sel_hi:[1,0]
	v_pk_mul_f32 v[116:117], v[114:115], v[122:123] op_sel_hi:[1,0]
	v_cvt_pk_bf16_f32 v114, v118, v119
	v_cvt_pk_bf16_f32 v115, v120, v121
	v_cvt_pk_bf16_f32 v116, v116, v117
	v_cvt_pk_bf16_f32 v117, v124, v125
	v_lshl_add_u64 v[118:119], v[148:149], 1, v[152:153]
	global_store_dwordx4 v[118:119], v[114:117], off offset:256 sc1
.LBB0_1428:
	s_or_b64 exec, exec, s[50:51]
	s_nop 0
	v_or_b32_e32 v114, 16, v150
	v_ashrrev_i32_e32 v115, 31, v114
	v_lshlrev_b64 v[116:117], 5, v[114:115]
	v_mad_i64_i32 v[114:115], s[50:51], v114, s63, 0
	v_lshl_add_u64 v[116:117], s[12:13], 0, v[116:117]
	v_lshl_add_u64 v[114:115], s[10:11], 0, v[114:115]
	s_and_saveexec_b64 s[50:51], vcc
	s_cbranch_execz .LBB0_1430
	global_load_dwordx4 v[118:121], v[116:117], off
	global_load_dwordx4 v[122:125], v[116:117], off offset:16
	s_waitcnt vmcnt(0)
	v_mov_b32_e32 v126, v118
	v_mov_b32_e32 v127, v122
	v_mov_b32_e32 v122, v119
	v_mov_b32_e32 v118, v120
	v_mov_b32_e32 v119, v124
	v_mov_b32_e32 v124, v121
	v_pk_add_f32 v[120:121], v[126:127], v[122:123]
	v_pk_add_f32 v[118:119], v[118:119], v[124:125]
	s_nop 0
	v_pk_add_f32 v[118:119], v[120:121], v[118:119]
	s_nop 0
	v_add_f32_e32 v118, v118, v119
	v_fmamk_f32 v118, v118, 0x3a800000, v162
	v_rsq_f32_e32 v118, v118
	s_nop 0
	v_pk_mul_f32 v[112:113], v[112:113], v[118:119] op_sel_hi:[1,0]
	v_pk_mul_f32 v[110:111], v[110:111], v[118:119] op_sel_hi:[1,0]
	v_pk_mul_f32 v[120:121], v[108:109], v[118:119] op_sel_hi:[1,0]
	v_pk_mul_f32 v[108:109], v[106:107], v[118:119] op_sel_hi:[1,0]
	v_cvt_pk_bf16_f32 v106, v110, v111
	v_cvt_pk_bf16_f32 v107, v112, v113
	v_cvt_pk_bf16_f32 v108, v108, v109
	v_cvt_pk_bf16_f32 v109, v120, v121
	v_lshl_add_u64 v[110:111], v[148:149], 1, v[114:115]
	global_store_dwordx4 v[110:111], v[106:109], off sc1
.LBB0_1430:
	s_or_b64 exec, exec, s[50:51]
	s_and_saveexec_b64 s[50:51], s[6:7]
	s_cbranch_execz .LBB0_1432
	global_load_dwordx4 v[106:109], v[116:117], off
	global_load_dwordx4 v[110:113], v[116:117], off offset:16
	s_waitcnt vmcnt(0)
	v_mov_b32_e32 v116, v106
	v_mov_b32_e32 v117, v110
	v_mov_b32_e32 v110, v107
	v_mov_b32_e32 v106, v108
	v_mov_b32_e32 v107, v112
	v_mov_b32_e32 v112, v109
	v_pk_add_f32 v[108:109], v[116:117], v[110:111]
	v_pk_add_f32 v[106:107], v[106:107], v[112:113]
	s_nop 0
	v_pk_add_f32 v[106:107], v[108:109], v[106:107]
	s_nop 0
	v_add_f32_e32 v106, v106, v107
	v_fmamk_f32 v106, v106, 0x3a800000, v162
	v_rsq_f32_e32 v106, v106
	s_nop 0
	v_pk_mul_f32 v[104:105], v[104:105], v[106:107] op_sel_hi:[1,0]
	v_pk_mul_f32 v[102:103], v[102:103], v[106:107] op_sel_hi:[1,0]
	v_pk_mul_f32 v[108:109], v[100:101], v[106:107] op_sel_hi:[1,0]
	v_pk_mul_f32 v[100:101], v[98:99], v[106:107] op_sel_hi:[1,0]
	v_cvt_pk_bf16_f32 v98, v102, v103
	v_cvt_pk_bf16_f32 v99, v104, v105
	v_cvt_pk_bf16_f32 v100, v100, v101
	v_cvt_pk_bf16_f32 v101, v108, v109
	v_lshl_add_u64 v[102:103], v[148:149], 1, v[114:115]
	global_store_dwordx4 v[102:103], v[98:101], off offset:256 sc1
.LBB0_1432:
	s_or_b64 exec, exec, s[50:51]
	s_nop 0
	v_or_b32_e32 v98, 32, v150
	v_ashrrev_i32_e32 v99, 31, v98
	v_lshlrev_b64 v[100:101], 5, v[98:99]
	v_mad_i64_i32 v[98:99], s[50:51], v98, s63, 0
	v_lshl_add_u64 v[100:101], s[12:13], 0, v[100:101]
	v_lshl_add_u64 v[98:99], s[10:11], 0, v[98:99]
	s_and_saveexec_b64 s[50:51], vcc
	s_cbranch_execz .LBB0_1434
	global_load_dwordx4 v[102:105], v[100:101], off
	global_load_dwordx4 v[106:109], v[100:101], off offset:16
	s_waitcnt vmcnt(0)
	v_mov_b32_e32 v110, v102
	v_mov_b32_e32 v111, v106
	v_mov_b32_e32 v106, v103
	v_mov_b32_e32 v102, v104
	v_mov_b32_e32 v103, v108
	v_mov_b32_e32 v108, v105
	v_pk_add_f32 v[104:105], v[110:111], v[106:107]
	v_pk_add_f32 v[102:103], v[102:103], v[108:109]
	s_nop 0
	v_pk_add_f32 v[102:103], v[104:105], v[102:103]
	s_nop 0
	v_add_f32_e32 v102, v102, v103
	v_fmamk_f32 v102, v102, 0x3a800000, v162
	v_rsq_f32_e32 v102, v102
	s_nop 0
	v_pk_mul_f32 v[96:97], v[96:97], v[102:103] op_sel_hi:[1,0]
	v_pk_mul_f32 v[94:95], v[94:95], v[102:103] op_sel_hi:[1,0]
	v_pk_mul_f32 v[104:105], v[92:93], v[102:103] op_sel_hi:[1,0]
	v_pk_mul_f32 v[92:93], v[90:91], v[102:103] op_sel_hi:[1,0]
	v_cvt_pk_bf16_f32 v90, v94, v95
	v_cvt_pk_bf16_f32 v91, v96, v97
	v_cvt_pk_bf16_f32 v92, v92, v93
	v_cvt_pk_bf16_f32 v93, v104, v105
	v_lshl_add_u64 v[94:95], v[148:149], 1, v[98:99]
	global_store_dwordx4 v[94:95], v[90:93], off sc1
.LBB0_1434:
	s_or_b64 exec, exec, s[50:51]
	s_and_saveexec_b64 s[50:51], s[6:7]
	s_cbranch_execz .LBB0_1436
	global_load_dwordx4 v[90:93], v[100:101], off
	global_load_dwordx4 v[94:97], v[100:101], off offset:16
	s_waitcnt vmcnt(0)
	v_mov_b32_e32 v100, v90
	v_mov_b32_e32 v101, v94
	v_mov_b32_e32 v94, v91
	v_mov_b32_e32 v90, v92
	v_mov_b32_e32 v91, v96
	v_mov_b32_e32 v96, v93
	v_pk_add_f32 v[92:93], v[100:101], v[94:95]
	v_pk_add_f32 v[90:91], v[90:91], v[96:97]
	s_nop 0
	v_pk_add_f32 v[90:91], v[92:93], v[90:91]
	s_nop 0
	v_add_f32_e32 v90, v90, v91
	v_fmamk_f32 v90, v90, 0x3a800000, v162
	v_rsq_f32_e32 v90, v90
	s_nop 0
	v_pk_mul_f32 v[88:89], v[88:89], v[90:91] op_sel_hi:[1,0]
	v_pk_mul_f32 v[86:87], v[86:87], v[90:91] op_sel_hi:[1,0]
	v_pk_mul_f32 v[92:93], v[84:85], v[90:91] op_sel_hi:[1,0]
	v_pk_mul_f32 v[84:85], v[82:83], v[90:91] op_sel_hi:[1,0]
	v_cvt_pk_bf16_f32 v82, v86, v87
	v_cvt_pk_bf16_f32 v83, v88, v89
	v_cvt_pk_bf16_f32 v84, v84, v85
	v_cvt_pk_bf16_f32 v85, v92, v93
	v_lshl_add_u64 v[86:87], v[148:149], 1, v[98:99]
	global_store_dwordx4 v[86:87], v[82:85], off offset:256 sc1
.LBB0_1436:
	s_or_b64 exec, exec, s[50:51]
	s_nop 0
	v_or_b32_e32 v82, 48, v150
	v_ashrrev_i32_e32 v83, 31, v82
	v_lshlrev_b64 v[84:85], 5, v[82:83]
	v_mad_i64_i32 v[82:83], s[50:51], v82, s63, 0
	v_lshl_add_u64 v[84:85], s[12:13], 0, v[84:85]
	v_lshl_add_u64 v[82:83], s[10:11], 0, v[82:83]
	s_and_saveexec_b64 s[50:51], vcc
	s_cbranch_execz .LBB0_1438
	global_load_dwordx4 v[86:89], v[84:85], off
	global_load_dwordx4 v[90:93], v[84:85], off offset:16
	s_waitcnt vmcnt(0)
	v_mov_b32_e32 v94, v86
	v_mov_b32_e32 v95, v90
	v_mov_b32_e32 v90, v87
	v_mov_b32_e32 v86, v88
	v_mov_b32_e32 v87, v92
	v_mov_b32_e32 v92, v89
	v_pk_add_f32 v[88:89], v[94:95], v[90:91]
	v_pk_add_f32 v[86:87], v[86:87], v[92:93]
	s_nop 0
	v_pk_add_f32 v[86:87], v[88:89], v[86:87]
	s_nop 0
	v_add_f32_e32 v86, v86, v87
	v_fmamk_f32 v86, v86, 0x3a800000, v162
	v_rsq_f32_e32 v86, v86
	s_nop 0
	v_pk_mul_f32 v[80:81], v[80:81], v[86:87] op_sel_hi:[1,0]
	v_pk_mul_f32 v[78:79], v[78:79], v[86:87] op_sel_hi:[1,0]
	v_pk_mul_f32 v[88:89], v[76:77], v[86:87] op_sel_hi:[1,0]
	v_pk_mul_f32 v[76:77], v[74:75], v[86:87] op_sel_hi:[1,0]
	v_cvt_pk_bf16_f32 v74, v78, v79
	v_cvt_pk_bf16_f32 v75, v80, v81
	v_cvt_pk_bf16_f32 v76, v76, v77
	v_cvt_pk_bf16_f32 v77, v88, v89
	v_lshl_add_u64 v[78:79], v[148:149], 1, v[82:83]
	global_store_dwordx4 v[78:79], v[74:77], off sc1
.LBB0_1438:
	s_or_b64 exec, exec, s[50:51]
	s_and_saveexec_b64 s[50:51], s[6:7]
	s_cbranch_execz .LBB0_1440
	global_load_dwordx4 v[74:77], v[84:85], off
	global_load_dwordx4 v[78:81], v[84:85], off offset:16
	s_waitcnt vmcnt(0)
	v_mov_b32_e32 v84, v74
	v_mov_b32_e32 v85, v78
	v_mov_b32_e32 v78, v75
	v_mov_b32_e32 v74, v76
	v_mov_b32_e32 v75, v80
	v_mov_b32_e32 v80, v77
	v_pk_add_f32 v[76:77], v[84:85], v[78:79]
	v_pk_add_f32 v[74:75], v[74:75], v[80:81]
	s_nop 0
	v_pk_add_f32 v[74:75], v[76:77], v[74:75]
	s_nop 0
	v_add_f32_e32 v74, v74, v75
	v_fmamk_f32 v74, v74, 0x3a800000, v162
	v_rsq_f32_e32 v74, v74
	s_nop 0
	v_pk_mul_f32 v[72:73], v[72:73], v[74:75] op_sel_hi:[1,0]
	v_pk_mul_f32 v[70:71], v[70:71], v[74:75] op_sel_hi:[1,0]
	v_pk_mul_f32 v[76:77], v[68:69], v[74:75] op_sel_hi:[1,0]
	v_pk_mul_f32 v[68:69], v[66:67], v[74:75] op_sel_hi:[1,0]
	v_cvt_pk_bf16_f32 v66, v70, v71
	v_cvt_pk_bf16_f32 v67, v72, v73
	v_cvt_pk_bf16_f32 v68, v68, v69
	v_cvt_pk_bf16_f32 v69, v76, v77
	v_lshl_add_u64 v[70:71], v[148:149], 1, v[82:83]
	global_store_dwordx4 v[70:71], v[66:69], off offset:256 sc1
.LBB0_1440:
	s_or_b64 exec, exec, s[50:51]
	s_nop 0
	v_add_u32_e32 v66, 0x80, v150
	v_ashrrev_i32_e32 v67, 31, v66
	v_lshlrev_b64 v[68:69], 5, v[66:67]
	v_mad_i64_i32 v[66:67], s[50:51], v66, s63, 0
	v_lshl_add_u64 v[68:69], s[12:13], 0, v[68:69]
	v_lshl_add_u64 v[66:67], s[10:11], 0, v[66:67]
	s_and_saveexec_b64 s[50:51], vcc
	s_cbranch_execz .LBB0_1442
	global_load_dwordx4 v[70:73], v[68:69], off
	global_load_dwordx4 v[74:77], v[68:69], off offset:16
	s_waitcnt vmcnt(0)
	v_mov_b32_e32 v78, v70
	v_mov_b32_e32 v79, v74
	v_mov_b32_e32 v74, v71
	v_mov_b32_e32 v70, v72
	v_mov_b32_e32 v71, v76
	v_mov_b32_e32 v76, v73
	v_pk_add_f32 v[72:73], v[78:79], v[74:75]
	v_pk_add_f32 v[70:71], v[70:71], v[76:77]
	s_nop 0
	v_pk_add_f32 v[70:71], v[72:73], v[70:71]
	s_nop 0
	v_add_f32_e32 v70, v70, v71
	v_fmamk_f32 v70, v70, 0x3a800000, v162
	v_rsq_f32_e32 v70, v70
	s_nop 0
	v_pk_mul_f32 v[64:65], v[64:65], v[70:71] op_sel_hi:[1,0]
	v_pk_mul_f32 v[62:63], v[62:63], v[70:71] op_sel_hi:[1,0]
	v_pk_mul_f32 v[72:73], v[60:61], v[70:71] op_sel_hi:[1,0]
	v_pk_mul_f32 v[60:61], v[58:59], v[70:71] op_sel_hi:[1,0]
	v_cvt_pk_bf16_f32 v58, v62, v63
	v_cvt_pk_bf16_f32 v59, v64, v65
	v_cvt_pk_bf16_f32 v60, v60, v61
	v_cvt_pk_bf16_f32 v61, v72, v73
	v_lshl_add_u64 v[62:63], v[148:149], 1, v[66:67]
	global_store_dwordx4 v[62:63], v[58:61], off sc1
.LBB0_1442:
	s_or_b64 exec, exec, s[50:51]
	s_and_saveexec_b64 s[50:51], s[6:7]
	s_cbranch_execz .LBB0_1444
	global_load_dwordx4 v[58:61], v[68:69], off
	global_load_dwordx4 v[62:65], v[68:69], off offset:16
	s_waitcnt vmcnt(0)
	v_mov_b32_e32 v68, v58
	v_mov_b32_e32 v69, v62
	v_mov_b32_e32 v62, v59
	v_mov_b32_e32 v58, v60
	v_mov_b32_e32 v59, v64
	v_mov_b32_e32 v64, v61
	v_pk_add_f32 v[60:61], v[68:69], v[62:63]
	v_pk_add_f32 v[58:59], v[58:59], v[64:65]
	s_nop 0
	v_pk_add_f32 v[58:59], v[60:61], v[58:59]
	s_nop 0
	v_add_f32_e32 v58, v58, v59
	v_fmamk_f32 v58, v58, 0x3a800000, v162
	v_rsq_f32_e32 v58, v58
	s_nop 0
	v_pk_mul_f32 v[56:57], v[56:57], v[58:59] op_sel_hi:[1,0]
	v_pk_mul_f32 v[54:55], v[54:55], v[58:59] op_sel_hi:[1,0]
	v_pk_mul_f32 v[60:61], v[52:53], v[58:59] op_sel_hi:[1,0]
	v_pk_mul_f32 v[52:53], v[50:51], v[58:59] op_sel_hi:[1,0]
	v_cvt_pk_bf16_f32 v50, v54, v55
	v_cvt_pk_bf16_f32 v51, v56, v57
	v_cvt_pk_bf16_f32 v52, v52, v53
	v_cvt_pk_bf16_f32 v53, v60, v61
	v_lshl_add_u64 v[54:55], v[148:149], 1, v[66:67]
	global_store_dwordx4 v[54:55], v[50:53], off offset:256 sc1
.LBB0_1444:
	s_or_b64 exec, exec, s[50:51]
	s_nop 0
	v_add_u32_e32 v50, 0x90, v150
	v_ashrrev_i32_e32 v51, 31, v50
	v_lshlrev_b64 v[52:53], 5, v[50:51]
	v_mad_i64_i32 v[50:51], s[50:51], v50, s63, 0
	v_lshl_add_u64 v[52:53], s[12:13], 0, v[52:53]
	v_lshl_add_u64 v[50:51], s[10:11], 0, v[50:51]
	s_and_saveexec_b64 s[50:51], vcc
	s_cbranch_execz .LBB0_1446
	global_load_dwordx4 v[54:57], v[52:53], off
	global_load_dwordx4 v[58:61], v[52:53], off offset:16
	s_waitcnt vmcnt(0)
	v_mov_b32_e32 v62, v54
	v_mov_b32_e32 v63, v58
	v_mov_b32_e32 v58, v55
	v_mov_b32_e32 v54, v56
	v_mov_b32_e32 v55, v60
	v_mov_b32_e32 v60, v57
	v_pk_add_f32 v[56:57], v[62:63], v[58:59]
	v_pk_add_f32 v[54:55], v[54:55], v[60:61]
	s_nop 0
	v_pk_add_f32 v[54:55], v[56:57], v[54:55]
	s_nop 0
	v_add_f32_e32 v54, v54, v55
	v_fmamk_f32 v54, v54, 0x3a800000, v162
	v_rsq_f32_e32 v54, v54
	s_nop 0
	v_pk_mul_f32 v[48:49], v[48:49], v[54:55] op_sel_hi:[1,0]
	v_pk_mul_f32 v[46:47], v[46:47], v[54:55] op_sel_hi:[1,0]
	v_pk_mul_f32 v[56:57], v[44:45], v[54:55] op_sel_hi:[1,0]
	v_pk_mul_f32 v[44:45], v[42:43], v[54:55] op_sel_hi:[1,0]
	v_cvt_pk_bf16_f32 v42, v46, v47
	v_cvt_pk_bf16_f32 v43, v48, v49
	v_cvt_pk_bf16_f32 v44, v44, v45
	v_cvt_pk_bf16_f32 v45, v56, v57
	v_lshl_add_u64 v[46:47], v[148:149], 1, v[50:51]
	global_store_dwordx4 v[46:47], v[42:45], off sc1
.LBB0_1446:
	s_or_b64 exec, exec, s[50:51]
	s_and_saveexec_b64 s[50:51], s[6:7]
	s_cbranch_execz .LBB0_1448
	global_load_dwordx4 v[42:45], v[52:53], off
	global_load_dwordx4 v[46:49], v[52:53], off offset:16
	s_waitcnt vmcnt(0)
	v_mov_b32_e32 v52, v42
	v_mov_b32_e32 v53, v46
	v_mov_b32_e32 v46, v43
	v_mov_b32_e32 v42, v44
	v_mov_b32_e32 v43, v48
	v_mov_b32_e32 v48, v45
	v_pk_add_f32 v[44:45], v[52:53], v[46:47]
	v_pk_add_f32 v[42:43], v[42:43], v[48:49]
	s_nop 0
	v_pk_add_f32 v[42:43], v[44:45], v[42:43]
	s_nop 0
	v_add_f32_e32 v42, v42, v43
	v_fmamk_f32 v42, v42, 0x3a800000, v162
	v_rsq_f32_e32 v42, v42
	s_nop 0
	v_pk_mul_f32 v[40:41], v[40:41], v[42:43] op_sel_hi:[1,0]
	v_pk_mul_f32 v[38:39], v[38:39], v[42:43] op_sel_hi:[1,0]
	v_pk_mul_f32 v[44:45], v[36:37], v[42:43] op_sel_hi:[1,0]
	v_pk_mul_f32 v[36:37], v[34:35], v[42:43] op_sel_hi:[1,0]
	v_cvt_pk_bf16_f32 v34, v38, v39
	v_cvt_pk_bf16_f32 v35, v40, v41
	v_cvt_pk_bf16_f32 v36, v36, v37
	v_cvt_pk_bf16_f32 v37, v44, v45
	v_lshl_add_u64 v[38:39], v[148:149], 1, v[50:51]
	global_store_dwordx4 v[38:39], v[34:37], off offset:256 sc1
.LBB0_1448:
	s_or_b64 exec, exec, s[50:51]
	s_nop 0
	v_add_u32_e32 v34, 0xa0, v150
	v_ashrrev_i32_e32 v35, 31, v34
	v_lshlrev_b64 v[36:37], 5, v[34:35]
	v_mad_i64_i32 v[34:35], s[50:51], v34, s63, 0
	v_lshl_add_u64 v[36:37], s[12:13], 0, v[36:37]
	v_lshl_add_u64 v[34:35], s[10:11], 0, v[34:35]
	s_and_saveexec_b64 s[50:51], vcc
	s_cbranch_execz .LBB0_1450
	global_load_dwordx4 v[38:41], v[36:37], off
	global_load_dwordx4 v[42:45], v[36:37], off offset:16
	s_waitcnt vmcnt(0)
	v_mov_b32_e32 v46, v38
	v_mov_b32_e32 v47, v42
	v_mov_b32_e32 v42, v39
	v_mov_b32_e32 v38, v40
	v_mov_b32_e32 v39, v44
	v_mov_b32_e32 v44, v41
	v_pk_add_f32 v[40:41], v[46:47], v[42:43]
	v_pk_add_f32 v[38:39], v[38:39], v[44:45]
	s_nop 0
	v_pk_add_f32 v[38:39], v[40:41], v[38:39]
	s_nop 0
	v_add_f32_e32 v38, v38, v39
	v_fmamk_f32 v38, v38, 0x3a800000, v162
	v_rsq_f32_e32 v38, v38
	s_nop 0
	v_pk_mul_f32 v[32:33], v[32:33], v[38:39] op_sel_hi:[1,0]
	v_pk_mul_f32 v[30:31], v[30:31], v[38:39] op_sel_hi:[1,0]
	v_pk_mul_f32 v[40:41], v[28:29], v[38:39] op_sel_hi:[1,0]
	v_pk_mul_f32 v[28:29], v[26:27], v[38:39] op_sel_hi:[1,0]
	v_cvt_pk_bf16_f32 v26, v30, v31
	v_cvt_pk_bf16_f32 v27, v32, v33
	v_cvt_pk_bf16_f32 v28, v28, v29
	v_cvt_pk_bf16_f32 v29, v40, v41
	v_lshl_add_u64 v[30:31], v[148:149], 1, v[34:35]
	global_store_dwordx4 v[30:31], v[26:29], off sc1
.LBB0_1450:
	s_or_b64 exec, exec, s[50:51]
	s_and_saveexec_b64 s[50:51], s[6:7]
	s_cbranch_execz .LBB0_1452
	global_load_dwordx4 v[26:29], v[36:37], off
	global_load_dwordx4 v[30:33], v[36:37], off offset:16
	s_waitcnt vmcnt(0)
	v_mov_b32_e32 v36, v26
	v_mov_b32_e32 v37, v30
	v_mov_b32_e32 v30, v27
	v_mov_b32_e32 v26, v28
	v_mov_b32_e32 v27, v32
	v_mov_b32_e32 v32, v29
	v_pk_add_f32 v[28:29], v[36:37], v[30:31]
	v_pk_add_f32 v[26:27], v[26:27], v[32:33]
	s_nop 0
	v_pk_add_f32 v[26:27], v[28:29], v[26:27]
	s_nop 0
	v_add_f32_e32 v26, v26, v27
	v_fmamk_f32 v26, v26, 0x3a800000, v162
	v_rsq_f32_e32 v26, v26
	s_nop 0
	v_pk_mul_f32 v[24:25], v[24:25], v[26:27] op_sel_hi:[1,0]
	v_pk_mul_f32 v[22:23], v[22:23], v[26:27] op_sel_hi:[1,0]
	v_pk_mul_f32 v[28:29], v[20:21], v[26:27] op_sel_hi:[1,0]
	v_pk_mul_f32 v[20:21], v[18:19], v[26:27] op_sel_hi:[1,0]
	v_cvt_pk_bf16_f32 v18, v22, v23
	v_cvt_pk_bf16_f32 v19, v24, v25
	v_cvt_pk_bf16_f32 v20, v20, v21
	v_cvt_pk_bf16_f32 v21, v28, v29
	v_lshl_add_u64 v[22:23], v[148:149], 1, v[34:35]
	global_store_dwordx4 v[22:23], v[18:21], off offset:256 sc1
.LBB0_1452:
	s_or_b64 exec, exec, s[50:51]
	s_nop 0
	v_add_u32_e32 v18, 0xb0, v150
	v_ashrrev_i32_e32 v19, 31, v18
	v_lshlrev_b64 v[20:21], 5, v[18:19]
	v_mad_i64_i32 v[18:19], s[50:51], v18, s63, 0
	v_lshl_add_u64 v[20:21], s[12:13], 0, v[20:21]
	v_lshl_add_u64 v[18:19], s[10:11], 0, v[18:19]
	s_and_saveexec_b64 s[50:51], vcc
	s_cbranch_execz .LBB0_1455
	global_load_dwordx4 v[22:25], v[20:21], off
	global_load_dwordx4 v[26:29], v[20:21], off offset:16
	s_waitcnt vmcnt(0)
	v_mov_b32_e32 v30, v22
	v_mov_b32_e32 v31, v26
	v_mov_b32_e32 v26, v23
	v_mov_b32_e32 v22, v24
	v_mov_b32_e32 v23, v28
	v_mov_b32_e32 v28, v25
	v_pk_add_f32 v[24:25], v[30:31], v[26:27]
	v_pk_add_f32 v[22:23], v[22:23], v[28:29]
	s_nop 0
	v_pk_add_f32 v[22:23], v[24:25], v[22:23]
	s_nop 0
	v_add_f32_e32 v22, v22, v23
	v_fmamk_f32 v22, v22, 0x3a800000, v162
	v_rsq_f32_e32 v22, v22
	s_nop 0
	v_pk_mul_f32 v[16:17], v[16:17], v[22:23] op_sel_hi:[1,0]
	v_pk_mul_f32 v[14:15], v[14:15], v[22:23] op_sel_hi:[1,0]
	v_pk_mul_f32 v[24:25], v[12:13], v[22:23] op_sel_hi:[1,0]
	v_pk_mul_f32 v[12:13], v[10:11], v[22:23] op_sel_hi:[1,0]
	v_cvt_pk_bf16_f32 v10, v14, v15
	v_cvt_pk_bf16_f32 v11, v16, v17
	v_cvt_pk_bf16_f32 v12, v12, v13
	v_cvt_pk_bf16_f32 v13, v24, v25
	v_lshl_add_u64 v[14:15], v[148:149], 1, v[18:19]
	global_store_dwordx4 v[14:15], v[10:13], off sc1
	s_or_b64 exec, exec, s[50:51]
	s_and_saveexec_b64 s[50:51], s[6:7]
	s_cbranch_execnz .LBB0_1456

.LBB0_1456:
	global_load_dwordx4 v[10:13], v[20:21], off
	global_load_dwordx4 v[14:17], v[20:21], off offset:16
	s_waitcnt vmcnt(0)
	v_mov_b32_e32 v20, v10
	v_mov_b32_e32 v21, v14
	v_mov_b32_e32 v14, v11
	v_mov_b32_e32 v10, v12
	v_mov_b32_e32 v11, v16
	v_mov_b32_e32 v16, v13
	v_pk_add_f32 v[12:13], v[20:21], v[14:15]
	v_pk_add_f32 v[10:11], v[10:11], v[16:17]
	s_nop 0
	v_pk_add_f32 v[10:11], v[12:13], v[10:11]
	s_nop 0
	v_add_f32_e32 v10, v10, v11
	v_fmamk_f32 v10, v10, 0x3a800000, v162
	v_rsq_f32_e32 v10, v10
	s_nop 0
	v_pk_mul_f32 v[8:9], v[8:9], v[10:11] op_sel_hi:[1,0]
	v_pk_mul_f32 v[6:7], v[6:7], v[10:11] op_sel_hi:[1,0]
	v_pk_mul_f32 v[12:13], v[4:5], v[10:11] op_sel_hi:[1,0]
	v_pk_mul_f32 v[4:5], v[2:3], v[10:11] op_sel_hi:[1,0]
	v_cvt_pk_bf16_f32 v2, v6, v7
	v_cvt_pk_bf16_f32 v3, v8, v9
	v_cvt_pk_bf16_f32 v4, v4, v5
	v_cvt_pk_bf16_f32 v5, v12, v13
	v_lshl_add_u64 v[6:7], v[148:149], 1, v[18:19]
	global_store_dwordx4 v[6:7], v[2:5], off offset:256 sc1
	s_or_b64 exec, exec, s[50:51]
	s_andn2_b64 vcc, exec, s[4:5]
	s_mov_b64 s[4:5], -1
	s_cbranch_vccnz .LBB0_1417

.LBB0_3200:
	v_lshl_add_u32 v150, s46, 8, v152
	v_add_u32_e32 v149, 0xffffc000, v150
	v_ashrrev_i32_e32 v151, 31, v150
	v_cmp_gt_i32_e32 vcc, s54, v150
	v_lshl_or_b32 v148, s64, 8, v154
	v_mov_b32_e32 v160, s8
	v_cndmask_b32_e32 v159, 0, v151, vcc
	v_cndmask_b32_e32 v158, v149, v150, vcc
	v_lshlrev_b64 v[162:163], 12, v[158:159]
	v_mov_b32_e32 v158, s9
	v_mov_b32_e32 v159, s7
	v_mov_b32_e32 v161, s6
	v_cndmask_b32_e32 v165, v158, v159, vcc
	v_cndmask_b32_e32 v164, v160, v161, vcc
	v_ashrrev_i32_e32 v149, 31, v148
	v_lshl_add_u64 v[162:163], v[164:165], 0, v[162:163]
	v_lshlrev_b64 v[148:149], 2, v[148:149]
	v_lshl_add_u64 v[170:171], v[162:163], 0, v[148:149]
	global_load_dwordx4 v[162:165], v[170:171], off
	global_load_dwordx4 v[166:169], v[170:171], off offset:16
	v_lshlrev_b64 v[172:173], 12, v[150:151]
	v_lshl_add_u64 v[172:173], s[6:7], 0, v[172:173]
	v_lshl_add_u64 v[172:173], v[172:173], 0, v[148:149]
	v_add_u32_e32 v151, 0xffffc010, v150
	s_waitcnt vmcnt(0)
	v_pk_add_f32 v[128:129], v[128:129], v[164:165]
	v_pk_add_f32 v[126:127], v[126:127], v[162:163]
	v_pk_add_f32 v[124:125], v[124:125], v[168:169]
	v_pk_add_f32 v[122:123], v[122:123], v[166:167]
	global_store_dwordx4 v[172:173], v[126:129], off sc1
	global_store_dwordx4 v[172:173], v[122:125], off offset:16 sc1
	global_load_dwordx4 v[122:125], v[170:171], off offset:512
	s_nop 0
	global_load_dwordx4 v[126:129], v[170:171], off offset:528
	v_or_b32_e32 v162, 16, v150
	v_ashrrev_i32_e32 v163, 31, v162
	v_cmp_gt_i32_e32 vcc, s54, v162
	s_waitcnt vmcnt(1)
	v_pk_add_f32 v[116:117], v[116:117], v[124:125]
	v_cndmask_b32_e32 v165, 0, v163, vcc
	v_cndmask_b32_e32 v164, v151, v162, vcc
	v_cndmask_b32_e32 v167, v158, v159, vcc
	v_cndmask_b32_e32 v166, v160, v161, vcc
	v_lshlrev_b64 v[164:165], 12, v[164:165]
	v_lshl_add_u64 v[164:165], v[166:167], 0, v[164:165]
	v_pk_add_f32 v[114:115], v[114:115], v[122:123]
	v_lshl_add_u64 v[164:165], v[164:165], 0, v[148:149]
	s_waitcnt vmcnt(0)
	v_pk_add_f32 v[112:113], v[112:113], v[128:129]
	v_pk_add_f32 v[110:111], v[110:111], v[126:127]
	global_store_dwordx4 v[172:173], v[114:117], off offset:512 sc1
	global_store_dwordx4 v[172:173], v[110:113], off offset:528 sc1
	global_load_dwordx4 v[110:113], v[164:165], off
	s_nop 0
	global_load_dwordx4 v[114:117], v[164:165], off offset:16
	v_lshlrev_b64 v[122:123], 12, v[162:163]
	v_lshl_add_u64 v[122:123], s[6:7], 0, v[122:123]
	v_lshl_add_u64 v[122:123], v[122:123], 0, v[148:149]
	s_waitcnt vmcnt(1)
	v_pk_add_f32 v[112:113], v[120:121], v[112:113]
	v_pk_add_f32 v[110:111], v[118:119], v[110:111]
	s_waitcnt vmcnt(0)
	v_pk_add_f32 v[108:109], v[108:109], v[116:117]
	v_pk_add_f32 v[106:107], v[106:107], v[114:115]
	global_store_dwordx4 v[122:123], v[110:113], off sc1
	global_store_dwordx4 v[122:123], v[106:109], off offset:16 sc1
	global_load_dwordx4 v[106:109], v[164:165], off offset:512
	s_nop 0
	global_load_dwordx4 v[110:113], v[164:165], off offset:528
	v_or_b32_e32 v114, 32, v150
	v_add_u32_e32 v116, 0xffffc020, v150
	v_ashrrev_i32_e32 v115, 31, v114
	v_cmp_gt_i32_e32 vcc, s54, v114
	s_waitcnt vmcnt(1)
	v_pk_add_f32 v[100:101], v[100:101], v[108:109]
	v_cndmask_b32_e32 v117, 0, v115, vcc
	v_cndmask_b32_e32 v116, v116, v114, vcc
	v_cndmask_b32_e32 v119, v158, v159, vcc
	v_cndmask_b32_e32 v118, v160, v161, vcc
	v_lshlrev_b64 v[116:117], 12, v[116:117]
	v_lshl_add_u64 v[116:117], v[118:119], 0, v[116:117]
	v_pk_add_f32 v[98:99], v[98:99], v[106:107]
	v_lshl_add_u64 v[116:117], v[116:117], 0, v[148:149]
	s_waitcnt vmcnt(0)
	v_pk_add_f32 v[96:97], v[96:97], v[112:113]
	v_pk_add_f32 v[94:95], v[94:95], v[110:111]
	global_store_dwordx4 v[122:123], v[98:101], off offset:512 sc1
	global_store_dwordx4 v[122:123], v[94:97], off offset:528 sc1
	global_load_dwordx4 v[94:97], v[116:117], off
	s_nop 0
	global_load_dwordx4 v[98:101], v[116:117], off offset:16
	v_lshlrev_b64 v[106:107], 12, v[114:115]
	v_lshl_add_u64 v[106:107], s[6:7], 0, v[106:107]
	v_lshl_add_u64 v[106:107], v[106:107], 0, v[148:149]
	s_waitcnt vmcnt(1)
	v_pk_add_f32 v[96:97], v[104:105], v[96:97]
	v_pk_add_f32 v[94:95], v[102:103], v[94:95]
	s_waitcnt vmcnt(0)
	v_pk_add_f32 v[92:93], v[92:93], v[100:101]
	v_pk_add_f32 v[90:91], v[90:91], v[98:99]
	global_store_dwordx4 v[106:107], v[94:97], off sc1
	global_store_dwordx4 v[106:107], v[90:93], off offset:16 sc1
	global_load_dwordx4 v[90:93], v[116:117], off offset:512
	s_nop 0
	global_load_dwordx4 v[94:97], v[116:117], off offset:528
	v_or_b32_e32 v98, 48, v150
	v_add_u32_e32 v100, 0xffffc030, v150
	v_ashrrev_i32_e32 v99, 31, v98
	v_cmp_gt_i32_e32 vcc, s54, v98
	s_waitcnt vmcnt(1)
	v_pk_add_f32 v[84:85], v[84:85], v[92:93]
	v_cndmask_b32_e32 v101, 0, v99, vcc
	v_cndmask_b32_e32 v100, v100, v98, vcc
	v_cndmask_b32_e32 v103, v158, v159, vcc
	v_cndmask_b32_e32 v102, v160, v161, vcc
	v_lshlrev_b64 v[100:101], 12, v[100:101]
	v_lshl_add_u64 v[100:101], v[102:103], 0, v[100:101]
	v_pk_add_f32 v[82:83], v[82:83], v[90:91]
	v_lshl_add_u64 v[100:101], v[100:101], 0, v[148:149]
	s_waitcnt vmcnt(0)
	v_pk_add_f32 v[80:81], v[80:81], v[96:97]
	v_pk_add_f32 v[78:79], v[78:79], v[94:95]
	global_store_dwordx4 v[106:107], v[82:85], off offset:512 sc1
	global_store_dwordx4 v[106:107], v[78:81], off offset:528 sc1
	global_load_dwordx4 v[78:81], v[100:101], off
	s_nop 0
	global_load_dwordx4 v[82:85], v[100:101], off offset:16
	v_lshlrev_b64 v[90:91], 12, v[98:99]
	v_lshl_add_u64 v[90:91], s[6:7], 0, v[90:91]
	v_lshl_add_u64 v[90:91], v[90:91], 0, v[148:149]
	v_cmp_gt_i32_e32 vcc, s60, v150
	s_waitcnt vmcnt(1)
	v_pk_add_f32 v[80:81], v[88:89], v[80:81]
	v_pk_add_f32 v[78:79], v[86:87], v[78:79]
	s_waitcnt vmcnt(0)
	v_pk_add_f32 v[76:77], v[76:77], v[84:85]
	v_pk_add_f32 v[74:75], v[74:75], v[82:83]
	global_store_dwordx4 v[90:91], v[78:81], off sc1
	global_store_dwordx4 v[90:91], v[74:77], off offset:16 sc1
	global_load_dwordx4 v[74:77], v[100:101], off offset:512
	s_nop 0
	global_load_dwordx4 v[78:81], v[100:101], off offset:528
	v_add_u32_e32 v82, 0x80, v150
	v_add_u32_e32 v84, 0xffffc080, v150
	v_ashrrev_i32_e32 v83, 31, v82
	v_cndmask_b32_e32 v85, 0, v83, vcc
	v_cndmask_b32_e32 v84, v84, v82, vcc
	v_cndmask_b32_e32 v87, v158, v159, vcc
	v_cndmask_b32_e32 v86, v160, v161, vcc
	v_lshlrev_b64 v[84:85], 12, v[84:85]
	v_lshl_add_u64 v[84:85], v[86:87], 0, v[84:85]
	v_lshl_add_u64 v[84:85], v[84:85], 0, v[148:149]
	v_cmp_gt_i32_e32 vcc, s61, v150
	s_waitcnt vmcnt(1)
	v_pk_add_f32 v[72:73], v[72:73], v[76:77]
	v_pk_add_f32 v[70:71], v[70:71], v[74:75]
	s_waitcnt vmcnt(0)
	v_pk_add_f32 v[68:69], v[68:69], v[80:81]
	v_pk_add_f32 v[66:67], v[66:67], v[78:79]
	global_store_dwordx4 v[90:91], v[70:73], off offset:512 sc1
	global_store_dwordx4 v[90:91], v[66:69], off offset:528 sc1
	global_load_dwordx4 v[66:69], v[84:85], off
	s_nop 0
	global_load_dwordx4 v[70:73], v[84:85], off offset:16
	v_lshlrev_b64 v[74:75], 12, v[82:83]
	v_lshl_add_u64 v[74:75], s[6:7], 0, v[74:75]
	v_lshl_add_u64 v[74:75], v[74:75], 0, v[148:149]
	s_waitcnt vmcnt(1)
	v_pk_add_f32 v[64:65], v[64:65], v[68:69]
	v_pk_add_f32 v[62:63], v[62:63], v[66:67]
	s_waitcnt vmcnt(0)
	v_pk_add_f32 v[60:61], v[60:61], v[72:73]
	v_pk_add_f32 v[58:59], v[58:59], v[70:71]
	global_store_dwordx4 v[74:75], v[62:65], off sc1
	global_store_dwordx4 v[74:75], v[58:61], off offset:16 sc1
	global_load_dwordx4 v[58:61], v[84:85], off offset:512
	s_nop 0
	global_load_dwordx4 v[62:65], v[84:85], off offset:528
	v_add_u32_e32 v66, 0x90, v150
	v_add_u32_e32 v68, 0xffffc090, v150
	v_ashrrev_i32_e32 v67, 31, v66
	v_cndmask_b32_e32 v69, 0, v67, vcc
	v_cndmask_b32_e32 v68, v68, v66, vcc
	v_cndmask_b32_e32 v71, v158, v159, vcc
	v_cndmask_b32_e32 v70, v160, v161, vcc
	v_lshlrev_b64 v[68:69], 12, v[68:69]
	v_lshl_add_u64 v[68:69], v[70:71], 0, v[68:69]
	v_lshl_add_u64 v[68:69], v[68:69], 0, v[148:149]
	v_cmp_gt_i32_e32 vcc, s62, v150
	s_waitcnt vmcnt(1)
	v_pk_add_f32 v[52:53], v[52:53], v[60:61]
	v_pk_add_f32 v[50:51], v[50:51], v[58:59]
	s_waitcnt vmcnt(0)
	v_pk_add_f32 v[48:49], v[48:49], v[64:65]
	v_pk_add_f32 v[46:47], v[46:47], v[62:63]
	global_store_dwordx4 v[74:75], v[50:53], off offset:512 sc1
	global_store_dwordx4 v[74:75], v[46:49], off offset:528 sc1
	global_load_dwordx4 v[46:49], v[68:69], off
	s_nop 0
	global_load_dwordx4 v[50:53], v[68:69], off offset:16
	v_lshlrev_b64 v[58:59], 12, v[66:67]
	v_lshl_add_u64 v[58:59], s[6:7], 0, v[58:59]
	v_lshl_add_u64 v[58:59], v[58:59], 0, v[148:149]
	s_waitcnt vmcnt(1)
	v_pk_add_f32 v[48:49], v[56:57], v[48:49]
	v_pk_add_f32 v[46:47], v[54:55], v[46:47]
	s_waitcnt vmcnt(0)
	v_pk_add_f32 v[44:45], v[44:45], v[52:53]
	v_pk_add_f32 v[42:43], v[42:43], v[50:51]
	global_store_dwordx4 v[58:59], v[46:49], off sc1
	global_store_dwordx4 v[58:59], v[42:45], off offset:16 sc1
	global_load_dwordx4 v[42:45], v[68:69], off offset:512
	s_nop 0
	global_load_dwordx4 v[46:49], v[68:69], off offset:528
	v_add_u32_e32 v50, 0xa0, v150
	v_add_u32_e32 v52, 0xffffc0a0, v150
	v_ashrrev_i32_e32 v51, 31, v50
	v_cndmask_b32_e32 v53, 0, v51, vcc
	v_cndmask_b32_e32 v52, v52, v50, vcc
	v_cndmask_b32_e32 v55, v158, v159, vcc
	v_cndmask_b32_e32 v54, v160, v161, vcc
	v_lshlrev_b64 v[52:53], 12, v[52:53]
	v_lshl_add_u64 v[52:53], v[54:55], 0, v[52:53]
	v_lshl_add_u64 v[52:53], v[52:53], 0, v[148:149]
	v_cmp_gt_i32_e32 vcc, s63, v150
	s_waitcnt vmcnt(1)
	v_pk_add_f32 v[36:37], v[36:37], v[44:45]
	v_pk_add_f32 v[34:35], v[34:35], v[42:43]
	s_waitcnt vmcnt(0)
	v_pk_add_f32 v[32:33], v[32:33], v[48:49]
	v_pk_add_f32 v[30:31], v[30:31], v[46:47]
	global_store_dwordx4 v[58:59], v[34:37], off offset:512 sc1
	global_store_dwordx4 v[58:59], v[30:33], off offset:528 sc1
	global_load_dwordx4 v[30:33], v[52:53], off
	s_nop 0
	global_load_dwordx4 v[34:37], v[52:53], off offset:16
	v_lshlrev_b64 v[42:43], 12, v[50:51]
	v_lshl_add_u64 v[42:43], s[6:7], 0, v[42:43]
	v_lshl_add_u64 v[42:43], v[42:43], 0, v[148:149]
	s_waitcnt vmcnt(1)
	v_pk_add_f32 v[32:33], v[40:41], v[32:33]
	v_pk_add_f32 v[30:31], v[38:39], v[30:31]
	s_waitcnt vmcnt(0)
	v_pk_add_f32 v[28:29], v[28:29], v[36:37]
	v_pk_add_f32 v[26:27], v[26:27], v[34:35]
	global_store_dwordx4 v[42:43], v[30:33], off sc1
	global_store_dwordx4 v[42:43], v[26:29], off offset:16 sc1
	global_load_dwordx4 v[26:29], v[52:53], off offset:512
	s_nop 0
	global_load_dwordx4 v[30:33], v[52:53], off offset:528
	v_add_u32_e32 v34, 0xb0, v150
	v_add_u32_e32 v36, 0xffffc0b0, v150
	v_ashrrev_i32_e32 v35, 31, v34
	v_cndmask_b32_e32 v37, 0, v35, vcc
	v_cndmask_b32_e32 v36, v36, v34, vcc
	v_cndmask_b32_e32 v39, v158, v159, vcc
	v_cndmask_b32_e32 v38, v160, v161, vcc
	v_lshlrev_b64 v[36:37], 12, v[36:37]
	v_lshl_add_u64 v[36:37], v[38:39], 0, v[36:37]
	v_lshl_add_u64 v[36:37], v[36:37], 0, v[148:149]
	s_andn2_b64 vcc, exec, s[0:1]
	s_mov_b64 s[0:1], -1
	s_waitcnt vmcnt(1)
	v_pk_add_f32 v[20:21], v[20:21], v[28:29]
	v_pk_add_f32 v[18:19], v[18:19], v[26:27]
	s_waitcnt vmcnt(0)
	v_pk_add_f32 v[16:17], v[16:17], v[32:33]
	v_pk_add_f32 v[14:15], v[14:15], v[30:31]
	global_store_dwordx4 v[42:43], v[18:21], off offset:512 sc1
	global_store_dwordx4 v[42:43], v[14:17], off offset:528 sc1
	global_load_dwordx4 v[14:17], v[36:37], off
	s_nop 0
	global_load_dwordx4 v[18:21], v[36:37], off offset:16
	v_lshlrev_b64 v[26:27], 12, v[34:35]
	v_lshl_add_u64 v[26:27], s[6:7], 0, v[26:27]
	v_lshl_add_u64 v[26:27], v[26:27], 0, v[148:149]
	s_waitcnt vmcnt(1)
	v_pk_add_f32 v[16:17], v[24:25], v[16:17]
	v_pk_add_f32 v[14:15], v[22:23], v[14:15]
	s_waitcnt vmcnt(0)
	v_pk_add_f32 v[12:13], v[12:13], v[20:21]
	v_pk_add_f32 v[10:11], v[10:11], v[18:19]
	global_store_dwordx4 v[26:27], v[14:17], off sc1
	global_store_dwordx4 v[26:27], v[10:13], off offset:16 sc1
	global_load_dwordx4 v[10:13], v[36:37], off offset:512
	s_nop 0
	global_load_dwordx4 v[14:17], v[36:37], off offset:528
	s_waitcnt vmcnt(1)
	v_pk_add_f32 v[8:9], v[8:9], v[12:13]
	v_pk_add_f32 v[6:7], v[6:7], v[10:11]
	s_waitcnt vmcnt(0)
	v_pk_add_f32 v[4:5], v[4:5], v[16:17]
	v_pk_add_f32 v[2:3], v[2:3], v[14:15]
	global_store_dwordx4 v[26:27], v[6:9], off offset:512 sc1
	global_store_dwordx4 v[26:27], v[2:5], off offset:528 sc1
	s_cbranch_vccnz .LBB0_3189
	s_andn2_b64 vcc, exec, s[10:11]
	s_cbranch_vccnz .LBB0_3188
	s_barrier
	s_branch .LBB0_3188

.LBB0_3207:
	v_add_co_u32_e32 v58, vcc, 0x1080000, v18
	s_nop 1
	v_addc_co_u32_e32 v59, vcc, 0, v19, vcc
	v_add_co_u32_e32 v60, vcc, 0x26e13000, v16
	s_nop 1
	v_addc_co_u32_e32 v61, vcc, 0, v17, vcc
	global_load_dwordx4 v[26:29], v[58:59], off
	global_load_dwordx4 v[94:97], v[60:61], off
	global_load_dwordx4 v[30:33], v[58:59], off offset:64
	global_load_dwordx4 v[98:101], v[60:61], off offset:64
	global_load_dwordx4 v[34:37], v[58:59], off offset:128
	global_load_dwordx4 v[102:105], v[60:61], off offset:128
	global_load_dwordx4 v[38:41], v[58:59], off offset:192
	global_load_dwordx4 v[106:109], v[60:61], off offset:192
	global_load_dwordx4 v[42:45], v[58:59], off offset:256
	global_load_dwordx4 v[110:113], v[60:61], off offset:256
	global_load_dwordx4 v[46:49], v[58:59], off offset:320
	global_load_dwordx4 v[114:117], v[60:61], off offset:320
	global_load_dwordx4 v[50:53], v[58:59], off offset:384
	global_load_dwordx4 v[118:121], v[60:61], off offset:384
	global_load_dwordx4 v[54:57], v[58:59], off offset:448
	global_load_dwordx4 v[122:125], v[60:61], off offset:448
	global_load_dwordx4 v[62:65], v[58:59], off offset:512
	global_load_dwordx4 v[126:129], v[60:61], off offset:512
	global_load_dwordx4 v[66:69], v[58:59], off offset:576
	global_load_dwordx4 v[130:133], v[60:61], off offset:576
	global_load_dwordx4 v[70:73], v[58:59], off offset:640
	global_load_dwordx4 v[134:137], v[60:61], off offset:640
	global_load_dwordx4 v[74:77], v[58:59], off offset:704
	global_load_dwordx4 v[138:141], v[60:61], off offset:704
	global_load_dwordx4 v[78:81], v[58:59], off offset:768
	global_load_dwordx4 v[142:145], v[60:61], off offset:768
	global_load_dwordx4 v[82:85], v[58:59], off offset:832
	global_load_dwordx4 v[148:151], v[60:61], off offset:832
	global_load_dwordx4 v[86:89], v[58:59], off offset:896
	global_load_dwordx4 v[152:155], v[60:61], off offset:896
	global_load_dwordx4 v[90:93], v[58:59], off offset:960
	global_load_dwordx4 v[156:159], v[60:61], off offset:960
	s_waitcnt vmcnt(30)
	v_mfma_f32_16x16x32_bf16 v[2:5], v[26:29], v[94:97], v[2:5]
	global_load_dwordx4 v[26:29], v[58:59], off offset:1024
	global_load_dwordx4 v[94:97], v[60:61], off offset:1024
	s_waitcnt vmcnt(30)
	v_mfma_f32_16x16x32_bf16 v[2:5], v[30:33], v[98:101], v[2:5]
	global_load_dwordx4 v[30:33], v[58:59], off offset:1088
	global_load_dwordx4 v[98:101], v[60:61], off offset:1088
	s_waitcnt vmcnt(30)
	v_mfma_f32_16x16x32_bf16 v[2:5], v[34:37], v[102:105], v[2:5]
	global_load_dwordx4 v[34:37], v[58:59], off offset:1152
	global_load_dwordx4 v[102:105], v[60:61], off offset:1152
	s_waitcnt vmcnt(30)
	v_mfma_f32_16x16x32_bf16 v[2:5], v[38:41], v[106:109], v[2:5]
	global_load_dwordx4 v[38:41], v[58:59], off offset:1216
	global_load_dwordx4 v[106:109], v[60:61], off offset:1216
	s_waitcnt vmcnt(30)
	v_mfma_f32_16x16x32_bf16 v[2:5], v[42:45], v[110:113], v[2:5]
	global_load_dwordx4 v[42:45], v[58:59], off offset:1280
	global_load_dwordx4 v[110:113], v[60:61], off offset:1280
	s_waitcnt vmcnt(30)
	v_mfma_f32_16x16x32_bf16 v[2:5], v[46:49], v[114:117], v[2:5]
	global_load_dwordx4 v[46:49], v[58:59], off offset:1344
	global_load_dwordx4 v[114:117], v[60:61], off offset:1344
	s_waitcnt vmcnt(30)
	v_mfma_f32_16x16x32_bf16 v[2:5], v[50:53], v[118:121], v[2:5]
	global_load_dwordx4 v[50:53], v[58:59], off offset:1408
	global_load_dwordx4 v[118:121], v[60:61], off offset:1408
	s_waitcnt vmcnt(30)
	v_mfma_f32_16x16x32_bf16 v[2:5], v[54:57], v[122:125], v[2:5]
	global_load_dwordx4 v[54:57], v[58:59], off offset:1472
	global_load_dwordx4 v[122:125], v[60:61], off offset:1472
	s_waitcnt vmcnt(30)
	v_mfma_f32_16x16x32_bf16 v[2:5], v[62:65], v[126:129], v[2:5]
	global_load_dwordx4 v[62:65], v[58:59], off offset:1536
	global_load_dwordx4 v[126:129], v[60:61], off offset:1536
	s_waitcnt vmcnt(30)
	v_mfma_f32_16x16x32_bf16 v[2:5], v[66:69], v[130:133], v[2:5]
	global_load_dwordx4 v[66:69], v[58:59], off offset:1600
	global_load_dwordx4 v[130:133], v[60:61], off offset:1600
	s_waitcnt vmcnt(30)
	v_mfma_f32_16x16x32_bf16 v[2:5], v[70:73], v[134:137], v[2:5]
	global_load_dwordx4 v[70:73], v[58:59], off offset:1664
	global_load_dwordx4 v[134:137], v[60:61], off offset:1664
	s_waitcnt vmcnt(30)
	v_mfma_f32_16x16x32_bf16 v[2:5], v[74:77], v[138:141], v[2:5]
	global_load_dwordx4 v[74:77], v[58:59], off offset:1728
	global_load_dwordx4 v[138:141], v[60:61], off offset:1728
	s_waitcnt vmcnt(30)
	v_mfma_f32_16x16x32_bf16 v[2:5], v[78:81], v[142:145], v[2:5]
	global_load_dwordx4 v[78:81], v[58:59], off offset:1792
	global_load_dwordx4 v[142:145], v[60:61], off offset:1792
	s_waitcnt vmcnt(30)
	v_mfma_f32_16x16x32_bf16 v[2:5], v[82:85], v[148:151], v[2:5]
	global_load_dwordx4 v[82:85], v[58:59], off offset:1856
	global_load_dwordx4 v[148:151], v[60:61], off offset:1856
	s_waitcnt vmcnt(30)
	v_mfma_f32_16x16x32_bf16 v[2:5], v[86:89], v[152:155], v[2:5]
	global_load_dwordx4 v[86:89], v[58:59], off offset:1920
	global_load_dwordx4 v[152:155], v[60:61], off offset:1920
	s_waitcnt vmcnt(30)
	v_mfma_f32_16x16x32_bf16 v[2:5], v[90:93], v[156:159], v[2:5]
	global_load_dwordx4 v[90:93], v[58:59], off offset:1984
	global_load_dwordx4 v[156:159], v[60:61], off offset:1984
	s_waitcnt vmcnt(30)
	v_mfma_f32_16x16x32_bf16 v[2:5], v[26:29], v[94:97], v[2:5]
	s_waitcnt vmcnt(28)
	v_mfma_f32_16x16x32_bf16 v[2:5], v[30:33], v[98:101], v[2:5]
	s_waitcnt vmcnt(26)
	v_mfma_f32_16x16x32_bf16 v[2:5], v[34:37], v[102:105], v[2:5]
	s_waitcnt vmcnt(24)
	v_mfma_f32_16x16x32_bf16 v[2:5], v[38:41], v[106:109], v[2:5]
	s_waitcnt vmcnt(22)
	v_mfma_f32_16x16x32_bf16 v[2:5], v[42:45], v[110:113], v[2:5]
	s_waitcnt vmcnt(20)
	v_mfma_f32_16x16x32_bf16 v[2:5], v[46:49], v[114:117], v[2:5]
	s_waitcnt vmcnt(18)
	v_mfma_f32_16x16x32_bf16 v[2:5], v[50:53], v[118:121], v[2:5]
	s_waitcnt vmcnt(16)
	v_mfma_f32_16x16x32_bf16 v[2:5], v[54:57], v[122:125], v[2:5]
	s_waitcnt vmcnt(14)
	v_mfma_f32_16x16x32_bf16 v[2:5], v[62:65], v[126:129], v[2:5]
	s_waitcnt vmcnt(12)
	v_mfma_f32_16x16x32_bf16 v[2:5], v[66:69], v[130:133], v[2:5]
	s_waitcnt vmcnt(10)
	v_mfma_f32_16x16x32_bf16 v[2:5], v[70:73], v[134:137], v[2:5]
	s_waitcnt vmcnt(8)
	v_mfma_f32_16x16x32_bf16 v[2:5], v[74:77], v[138:141], v[2:5]
	s_waitcnt vmcnt(6)
	v_mfma_f32_16x16x32_bf16 v[2:5], v[78:81], v[142:145], v[2:5]
	s_waitcnt vmcnt(4)
	v_mfma_f32_16x16x32_bf16 v[2:5], v[82:85], v[148:151], v[2:5]
	s_waitcnt vmcnt(2)
	v_mfma_f32_16x16x32_bf16 v[2:5], v[86:89], v[152:155], v[2:5]
	s_waitcnt vmcnt(0)
	v_mfma_f32_16x16x32_bf16 v[2:5], v[90:93], v[156:159], v[2:5]
	s_movk_i32 s0, 0x800
	s_nop 1
	v_lshl_or_b32 v18, s6, 4, v20
	v_ashrrev_i32_e32 v19, 31, v18
	v_lshlrev_b64 v[18:19], 2, v[18:19]
	v_lshl_add_u64 v[22:23], v[8:9], 0, v[18:19]
	global_load_dwordx4 v[22:25], v[22:23], off
	s_add_i32 s6, s6, s90
	s_cmp_gt_i32 s6, 63
	v_lshl_add_u64 v[18:19], v[10:11], 0, v[18:19]
	v_add_u32_e32 v14, s3, v14
	s_waitcnt vmcnt(0)
	v_pk_add_f32 v[4:5], v[4:5], v[24:25]
	v_pk_add_f32 v[2:3], v[2:3], v[22:23]
	global_store_dwordx4 v[18:19], v[2:5], off sc1
	s_cbranch_scc0 .LBB0_3206

.LBB0_3328:
	v_lshl_add_u32 v154, s22, 8, v147
	v_lshl_or_b32 v156, s69, 8, v149
	v_ashrrev_i32_e32 v155, 31, v154
	v_cvt_pk_bf16_f32 v126, v126, v127
	v_cvt_pk_bf16_f32 v127, v128, v129
	v_cvt_pk_bf16_f32 v128, v122, v123
	v_lshlrev_b64 v[122:123], 12, v[154:155]
	v_ashrrev_i32_e32 v157, 31, v156
	v_cvt_pk_bf16_f32 v129, v124, v125
	v_lshl_add_u64 v[122:123], s[6:7], 0, v[122:123]
	v_lshlrev_b64 v[124:125], 1, v[156:157]
	v_lshl_add_u64 v[122:123], v[122:123], 0, v[124:125]
	v_cvt_pk_bf16_f32 v110, v110, v111
	v_cvt_pk_bf16_f32 v111, v112, v113
	v_cvt_pk_bf16_f32 v112, v106, v107
	v_cvt_pk_bf16_f32 v113, v108, v109
	global_store_dwordx4 v[122:123], v[110:113], off offset:256 sc1
	v_cvt_pk_bf16_f32 v94, v94, v95
	v_cvt_pk_bf16_f32 v95, v96, v97
	v_or_b32_e32 v110, 16, v154
	v_ashrrev_i32_e32 v111, 31, v110
	v_lshlrev_b64 v[110:111], 12, v[110:111]
	v_lshl_add_u64 v[110:111], s[6:7], 0, v[110:111]
	v_lshl_add_u64 v[110:111], v[110:111], 0, v[124:125]
	v_cvt_pk_bf16_f32 v96, v90, v91
	v_cvt_pk_bf16_f32 v97, v92, v93
	global_store_dwordx4 v[110:111], v[94:97], off offset:256 sc1
	v_cvt_pk_bf16_f32 v62, v62, v63
	v_cvt_pk_bf16_f32 v63, v64, v65
	v_or_b32_e32 v94, 32, v154
	v_ashrrev_i32_e32 v95, 31, v94
	v_cvt_pk_bf16_f32 v65, v60, v61
	v_add_co_u32_e32 v60, vcc, s65, v122
	v_lshlrev_b64 v[94:95], 12, v[94:95]
	v_cvt_pk_bf16_f32 v64, v58, v59
	v_lshl_add_u64 v[58:59], v[122:123], 0, s[14:15]
	v_addc_co_u32_e32 v61, vcc, 0, v123, vcc
	v_cvt_pk_bf16_f32 v46, v46, v47
	v_cvt_pk_bf16_f32 v47, v48, v49
	v_cvt_pk_bf16_f32 v48, v42, v43
	v_cvt_pk_bf16_f32 v49, v44, v45
	v_lshl_add_u64 v[94:95], s[6:7], 0, v[94:95]
	global_store_dwordx4 v[58:59], v[46:49], off offset:256 sc1
	v_lshl_add_u64 v[94:95], v[94:95], 0, v[124:125]
	v_cvt_pk_bf16_f32 v78, v78, v79
	v_add_co_u32_e32 v48, vcc, s66, v122
	v_cvt_pk_bf16_f32 v79, v80, v81
	v_cvt_pk_bf16_f32 v80, v74, v75
	v_cvt_pk_bf16_f32 v81, v76, v77
	v_lshl_add_u64 v[46:47], v[122:123], 0, s[16:17]
	v_addc_co_u32_e32 v49, vcc, 0, v123, vcc
	v_cvt_pk_bf16_f32 v30, v30, v31
	v_cvt_pk_bf16_f32 v31, v32, v33
	v_cvt_pk_bf16_f32 v32, v26, v27
	v_cvt_pk_bf16_f32 v33, v28, v29
	global_store_dwordx4 v[94:95], v[78:81], off offset:256 sc1
	global_store_dwordx4 v[46:47], v[30:33], off offset:256 sc1
	v_cvt_pk_bf16_f32 v14, v14, v15
	v_or_b32_e32 v78, 48, v154
	v_add_co_u32_e32 v32, vcc, s67, v122
	v_ashrrev_i32_e32 v79, 31, v78
	v_lshl_add_u64 v[30:31], v[122:123], 0, s[18:19]
	v_addc_co_u32_e32 v33, vcc, 0, v123, vcc
	v_cvt_pk_bf16_f32 v15, v16, v17
	v_cvt_pk_bf16_f32 v16, v10, v11
	v_cvt_pk_bf16_f32 v17, v12, v13
	v_lshlrev_b64 v[78:79], 12, v[78:79]
	global_store_dwordx4 v[30:31], v[14:17], off offset:256 sc1
	v_lshl_add_u64 v[78:79], s[6:7], 0, v[78:79]
	v_cvt_pk_bf16_f32 v106, v118, v119
	v_add_co_u32_e32 v16, vcc, s68, v122
	v_cvt_pk_bf16_f32 v107, v120, v121
	s_nop 0
	v_addc_co_u32_e32 v17, vcc, 0, v123, vcc
	v_cvt_pk_bf16_f32 v108, v114, v115
	v_cvt_pk_bf16_f32 v109, v116, v117
	v_cvt_pk_bf16_f32 v90, v102, v103
	v_cvt_pk_bf16_f32 v91, v104, v105
	v_cvt_pk_bf16_f32 v92, v98, v99
	v_cvt_pk_bf16_f32 v93, v100, v101
	v_cvt_pk_bf16_f32 v74, v86, v87
	v_cvt_pk_bf16_f32 v75, v88, v89
	v_cvt_pk_bf16_f32 v76, v82, v83
	v_cvt_pk_bf16_f32 v77, v84, v85
	v_lshl_add_u64 v[78:79], v[78:79], 0, v[124:125]
	v_cvt_pk_bf16_f32 v70, v70, v71
	v_cvt_pk_bf16_f32 v71, v72, v73
	v_cvt_pk_bf16_f32 v72, v66, v67
	v_cvt_pk_bf16_f32 v73, v68, v69
	v_cvt_pk_bf16_f32 v42, v54, v55
	v_cvt_pk_bf16_f32 v43, v56, v57
	v_cvt_pk_bf16_f32 v44, v50, v51
	v_cvt_pk_bf16_f32 v45, v52, v53
	v_cvt_pk_bf16_f32 v26, v38, v39
	v_cvt_pk_bf16_f32 v27, v40, v41
	v_cvt_pk_bf16_f32 v28, v34, v35
	v_cvt_pk_bf16_f32 v29, v36, v37
	v_cvt_pk_bf16_f32 v10, v22, v23
	v_cvt_pk_bf16_f32 v11, v24, v25
	v_cvt_pk_bf16_f32 v12, v18, v19
	v_cvt_pk_bf16_f32 v13, v20, v21
	v_lshl_add_u64 v[14:15], v[122:123], 0, s[20:21]
	v_cvt_pk_bf16_f32 v6, v6, v7
	v_cvt_pk_bf16_f32 v7, v8, v9
	v_cvt_pk_bf16_f32 v8, v2, v3
	v_cvt_pk_bf16_f32 v9, v4, v5
	s_andn2_b64 vcc, exec, s[0:1]
	s_mov_b64 s[0:1], -1
	global_store_dwordx4 v[122:123], v[126:129], off sc1
	global_store_dwordx4 v[110:111], v[106:109], off sc1
	global_store_dwordx4 v[94:95], v[90:93], off sc1
	global_store_dwordx4 v[78:79], v[74:77], off sc1
	global_store_dwordx4 v[78:79], v[70:73], off offset:256 sc1
	global_store_dwordx4 v[60:61], v[62:65], off sc1
	global_store_dwordx4 v[48:49], v[42:45], off sc1
	global_store_dwordx4 v[32:33], v[26:29], off sc1
	global_store_dwordx4 v[16:17], v[10:13], off sc1
	global_store_dwordx4 v[14:15], v[6:9], off offset:256 sc1
	s_cbranch_vccnz .LBB0_3321
	s_andn2_b64 vcc, exec, s[8:9]
	s_cbranch_vccnz .LBB0_3320
	s_barrier
	s_branch .LBB0_3320
